# v11: + GLA sample-item load batching; odd-layer phase: half of the blocks run ma_ret before the HBM-bound state streaming so the two overlap chip-wide
# speedup vs baseline: 1.0754x; 1.0212x over previous
; __global__ void __launch_bounds__(NTHREADS, 2) fwd_megakernel(Params p) {
;     ...
;                 for (int it = bid; it < 512; it += G) sample_item<2>(p, lds, it);
;                 if (G == 256) { const int xq = bid & 7, yq = bid >> 3;
;                     for (int k = 0; k < 4; ++k) { const int q = k * 64 + xq * 8 + (yq >> 2); ma_ret_item(p, lds, q * 4 + (yq & 3)); } }
;                 else for (int it = bid; it < 1024; it += G) ma_ret_item(p, lds, it);
.LBB0_668:
	s_or_b64 exec, exec, s[0:1]
	v_readlane_b32 s0, v253, 28
	v_readlane_b32 s1, v253, 29
	v_readlane_b32 s12, v254, 45
	v_readlane_b32 s14, v254, 41
	s_andn2_b64 vcc, exec, s[0:1]
	v_readlane_b32 s13, v254, 46
	v_readlane_b32 s15, v254, 42
	s_mov_b32 s18, s2
	s_waitcnt lgkmcnt(0)
	s_barrier
	s_mov_b32 s99, 0
	s_bitcmp1_b32 s2, 3
	s_cbranch_scc0 .Lo1_normal_order
	s_mov_b32 s99, 1
	s_branch .LBB0_669
.Lo1_sample_second:
	s_mov_b32 s99, 2
	v_readlane_b32 s0, v253, 28
	v_readlane_b32 s1, v253, 29
	s_nop 4
	s_andn2_b64 vcc, exec, s[0:1]
	s_cbranch_vccnz .Lo1_phase_end
	v_readlane_b32 s12, v254, 45
	v_readlane_b32 s14, v254, 41
	v_readlane_b32 s13, v254, 46
	v_readlane_b32 s15, v254, 42
	s_mov_b32 s18, s2
	s_nop 4
	s_branch .LBB0_684
.Lo1_after_sample:
	s_cmp_eq_u32 s99, 2
	s_cbranch_scc1 .Lo1_phase_end
	s_branch .LBB0_669
.Lo1_normal_order:
	s_cbranch_vccz .LBB0_684

; __global__ void __launch_bounds__(NTHREADS, 2) fwd_megakernel(Params p) {
;     ...
;                 if (G == 256) { const int xq = bid & 7, yq = bid >> 3;
;                     for (int k = 0; k < 4; ++k) { const int q = k * 64 + xq * 8 + (yq >> 2); ma_ret_item(p, lds, q * 4 + (yq & 3)); } }
;                 else for (int it = bid; it < 1024; it += G) ma_ret_item(p, lds, it);
.LBB0_680:
	s_cmp_eq_u32 s99, 1
	s_cbranch_scc1 .Lo1_sample_second

; __device__ __forceinline__ unsigned pk2(float lo, float hi) { return pg8::cvt_pk_bf16(lo, hi); }
; __device__ __forceinline__ float siluf(float x) { return x * __builtin_amdgcn_rcpf(1.0f + __expf(-x)); }
; #define BSYNC() do { asm volatile("s_waitcnt vmcnt(0) lgkmcnt(0)" ::: "memory"); __syncthreads(); } while (0)
; template <int TY> __device__ __forceinline__ void mc_item(const Params& p, ldsp lds, int item) {
;     ...
;     float rstd[4];
; #pragma unroll
;     for (int tk = 0; tk < 4; ++tk) { float s = 0.f;
; #pragma unroll
;         for (int ei = 0; ei < ET; ++ei) { const f32x4 v = acc[ei][tk]; s += (v[0] * v[0] + v[1] * v[1]) + (v[2] * v[2] + v[3] * v[3]); }
;         s += __shfl_xor(s, 16); s += __shfl_xor(s, 32);
;         if (q4 == 0) RED[wave * 64 + 16 * tk + l15] = s; }
;     BSYNC();
; #pragma unroll
;     for (int tk = 0; tk < 4; ++tk) { float s = 0.f;
; #pragma unroll
;         for (int w = 0; w < 8; ++w) s += RED[w * 64 + 16 * tk + l15];
;         rstd[tk] = rsqrtf(s * (1.0f / DV) + EPS); }
;     const float* nwp = TY == 0 ? p.in[12] : (TY == 1 ? p.in[14] : p.in[17]);
;     const int goff = TY == 0 ? E_RA + h * 128 : (TY == 1 ? E_GB + h * 128 : O_G + h * 512);
;     constexpr int LDY = TY == 2 ? 2048 : 1024; const int ycol = TY == 0 ? h * 128 : (TY == 1 ? 512 + h * 128 : h * 512);
;     bf16_t* Y = (bf16_t*)(p.ws + WS_Y);
; #pragma unroll
;     for (int ei = 0; ei < ET; ++ei) { const int e0 = 16 * (wave * ET + ei) + 4 * q4; const f32x4 w4 = *(const f32x4*)(nwp + e0);
; #pragma unroll
;         for (int tk = 0; tk < 4; ++tk) { const size_t row = (size_t)row0 + 16 * tk + l15;
;             const u32x2 gw = *(const u32x2*)(Pb + row * PP + goff + e0);
;             const float g0 = bf2f(gw.x & 0xffffu), g1 = bf2f(gw.x >> 16), g2 = bf2f(gw.y & 0xffffu), g3 = bf2f(gw.y >> 16);
;             const f32x4 v = acc[ei][tk] * rstd[tk] * w4;
;             float y0 = v[0] * siluf(g0), y1 = v[1] * siluf(g1), y2 = v[2] * siluf(g2), y3 = v[3] * siluf(g3);
;     ...
;             if (!(fabsf(y0) < 1e30f)) y0 = 0.f; if (!(fabsf(y1) < 1e30f)) y1 = 0.f; if (!(fabsf(y2) < 1e30f)) y2 = 0.f; if (!(fabsf(y3) < 1e30f)) y3 = 0.f;
;     ...
;             u32x2 o; o.x = pk2(y0, y1); o.y = pk2(y2, y3);
;             *(u32x2*)(Y + row * LDY + ycol + e0) = o; } }
.LBB0_856:
	s_or_b64 exec, exec, s[0:1]
	v_or_b32_e32 v72, s8, v151
	s_lshl_b32 s8, s59, 1
	s_add_u32 s0, s26, s8
	s_addc_u32 s1, s27, 0
	v_or_b32_e32 v84, s58, v150
	v_mov_b64_e32 v[90:91], s[0:1]
	s_waitcnt lgkmcnt(0)
	v_mad_i64_i32 v[62:63], s[0:1], v84, s56, v[90:91]
	v_ashrrev_i32_e32 v73, 31, v72
	v_lshl_add_u64 v[74:75], v[62:63], 0, s[48:49]
	v_lshlrev_b64 v[82:83], 1, v[72:73]
	v_lshl_add_u64 v[76:77], v[74:75], 0, v[82:83]
	s_waitcnt vmcnt(0) lgkmcnt(0)
	s_barrier
	global_load_dwordx2 v[186:187], v[76:77], off
	v_lshl_add_u64 v[188:189], v[72:73], 2, s[62:63]
	global_load_dwordx4 v[190:193], v[188:189], off
	v_or_b32_e32 v194, s58, v146
	v_mad_i64_i32 v[196:197], s[0:1], v194, s56, v[90:91]
	v_lshl_add_u64 v[198:199], v[196:197], 0, s[48:49]
	v_lshl_add_u64 v[200:201], v[198:199], 0, v[82:83]
	global_load_dwordx2 v[202:203], v[200:201], off
	v_or_b32_e32 v204, 32, v84
	v_mad_i64_i32 v[206:207], s[0:1], v204, s56, v[90:91]
	v_lshl_add_u64 v[208:209], v[206:207], 0, s[48:49]
	v_lshl_add_u64 v[210:211], v[208:209], 0, v[82:83]
	v_or_b32_e32 v212, 48, v84
	global_load_dwordx2 v[214:215], v[210:211], off
	v_mad_i64_i32 v[216:217], s[0:1], v212, s56, v[90:91]
	v_lshl_add_u64 v[218:219], v[216:217], 0, s[48:49]
	v_lshl_add_u64 v[220:221], v[218:219], 0, v[82:83]
	global_load_dwordx2 v[222:223], v[220:221], off
	v_or_b32_e32 v224, 16, v72
	v_ashrrev_i32_e32 v225, 31, v224
	v_lshlrev_b64 v[226:227], 1, v[224:225]
	v_lshl_add_u64 v[228:229], v[74:75], 0, v[226:227]
	global_load_dwordx2 v[230:231], v[228:229], off
	global_load_dwordx4 v[232:235], v[188:189], off offset:64
	v_lshl_add_u64 v[236:237], v[198:199], 0, v[226:227]
	global_load_dwordx2 v[238:239], v[236:237], off
	v_lshl_add_u64 v[240:241], v[208:209], 0, v[226:227]
	global_load_dwordx2 v[242:243], v[240:241], off
	v_lshl_add_u64 v[244:245], v[218:219], 0, v[226:227]
	global_load_dwordx2 v[246:247], v[244:245], off
	v_or_b32_e32 v248, 32, v72
	v_ashrrev_i32_e32 v249, 31, v248
	v_lshlrev_b64 v[120:121], 1, v[248:249]
	v_lshl_add_u64 v[122:123], v[74:75], 0, v[120:121]
	global_load_dwordx2 v[124:125], v[122:123], off
	v_lshl_add_u64 v[126:127], v[198:199], 0, v[120:121]
	global_load_dwordx4 v[128:131], v[188:189], off offset:128
	global_load_dwordx2 v[132:133], v[126:127], off
	v_lshl_add_u64 v[134:135], v[208:209], 0, v[120:121]
	global_load_dwordx2 v[136:137], v[134:135], off
	v_lshl_add_u64 v[140:141], v[218:219], 0, v[120:121]
	global_load_dwordx2 v[142:143], v[140:141], off
	v_or_b32_e32 v144, 48, v72
	v_ashrrev_i32_e32 v145, 31, v144
	v_lshlrev_b64 v[148:149], 1, v[144:145]
	v_lshl_add_u64 v[152:153], v[74:75], 0, v[148:149]
	global_load_dwordx2 v[154:155], v[152:153], off
	v_lshl_add_u64 v[156:157], v[198:199], 0, v[148:149]
	global_load_dwordx4 v[172:175], v[188:189], off offset:192
	global_load_dwordx2 v[158:159], v[156:157], off
	v_lshl_add_u64 v[162:163], v[208:209], 0, v[148:149]
	global_load_dwordx2 v[166:167], v[162:163], off
	v_lshl_add_u64 v[176:177], v[218:219], 0, v[148:149]
	global_load_dwordx2 v[178:179], v[176:177], off
	v_lshl_add_u64 v[70:71], v[72:73], 2, s[62:63]
	v_lshl_add_u32 v16, v150, 2, 0
	v_add_u32_e32 v16, 0x24c00, v16
	ds_read2_b32 v[76:77], v16 offset1:16
	ds_read2_b32 v[80:81], v16 offset0:64 offset1:80
	ds_read2_b32 v[86:87], v16 offset0:128 offset1:144
	ds_read2_b32 v[108:109], v16 offset0:192 offset1:208
	v_add_u32_e32 v73, 0x400, v16
	s_waitcnt lgkmcnt(3)
	v_mov_b32_e32 v118, v77
	v_mov_b32_e32 v119, v76
	s_waitcnt lgkmcnt(2)
	v_mov_b32_e32 v76, v81
	v_mov_b32_e32 v77, v80
	s_waitcnt lgkmcnt(1)
	v_mov_b32_e32 v80, v87
	v_mov_b32_e32 v81, v86
	s_waitcnt lgkmcnt(0)
	v_mov_b32_e32 v86, v109
	v_mov_b32_e32 v87, v108
	v_pk_add_f32 v[108:109], v[118:119], 0 op_sel_hi:[1,0]
	ds_read2_b32 v[106:107], v16 offset0:32 offset1:48
	ds_read2_b32 v[102:103], v16 offset0:96 offset1:112
	ds_read2_b32 v[98:99], v16 offset0:160 offset1:176
	ds_read2_b32 v[94:95], v16 offset0:224 offset1:240
	ds_read2_b32 v[110:111], v73 offset1:16
	ds_read2_b32 v[112:113], v73 offset0:64 offset1:80
	ds_read2_b32 v[114:115], v73 offset0:128 offset1:144
	ds_read2_b32 v[116:117], v73 offset0:192 offset1:208
	ds_read2_b32 v[104:105], v73 offset0:32 offset1:48
	ds_read2_b32 v[100:101], v73 offset0:96 offset1:112
	ds_read2_b32 v[96:97], v73 offset0:160 offset1:176
	ds_read2_b32 v[92:93], v73 offset0:224 offset1:240
	v_pk_add_f32 v[76:77], v[108:109], v[76:77]
	s_waitcnt lgkmcnt(7)
	v_mov_b32_e32 v118, v111
	v_pk_add_f32 v[76:77], v[76:77], v[80:81]
	v_mov_b32_e32 v119, v110
	v_pk_add_f32 v[76:77], v[76:77], v[86:87]
	s_waitcnt lgkmcnt(6)
	v_mov_b32_e32 v110, v113
	v_mov_b32_e32 v111, v112
	v_pk_add_f32 v[76:77], v[76:77], v[118:119]
	s_waitcnt lgkmcnt(5)
	v_mov_b32_e32 v112, v115
	v_mov_b32_e32 v113, v114
	v_pk_add_f32 v[76:77], v[76:77], v[110:111]
	s_mov_b32 s0, 0x358637bd
	s_waitcnt lgkmcnt(4)
	v_mov_b32_e32 v114, v117
	v_mov_b32_e32 v115, v116
	v_pk_add_f32 v[76:77], v[76:77], v[112:113]
	v_mov_b64_e32 v[88:89], s[0:1]
	v_pk_add_f32 v[76:77], v[76:77], v[114:115]
	s_mov_b32 s10, 0x3b000000
	v_pk_fma_f32 v[76:77], v[76:77], s[10:11], v[88:89] op_sel_hi:[1,0,0]
	s_add_u32 s0, s61, s8
	v_mul_f32_e32 v16, 0x4b800000, v77
	v_cmp_gt_f32_e32 vcc, s33, v77
	v_readlane_b32 s1, v253, 31
	v_mov_b32_e32 v85, s9
	v_cndmask_b32_e32 v16, v77, v16, vcc
	v_rsq_f32_e32 v16, v16
	s_addc_u32 s1, s1, 0
	v_lshl_add_u64 v[86:87], s[0:1], 0, v[82:83]
	s_add_i32 s36, s36, 1
	v_mul_f32_e32 v73, 0x45800000, v16
	v_cndmask_b32_e32 v16, v16, v73, vcc
	v_pk_mul_f32 v[66:67], v[66:67], v[16:17] op_sel_hi:[1,0]
	v_pk_mul_f32 v[68:69], v[68:69], v[16:17] op_sel_hi:[1,0]
	v_cmp_gt_f32_e32 vcc, s33, v76
	v_pk_mul_f32 v[46:47], v[46:47], v[16:17] op_sel_hi:[1,0]
	v_pk_mul_f32 v[48:49], v[48:49], v[16:17] op_sel_hi:[1,0]
	v_pk_mul_f32 v[30:31], v[30:31], v[16:17] op_sel_hi:[1,0]
	v_pk_mul_f32 v[32:33], v[32:33], v[16:17] op_sel_hi:[1,0]
	v_pk_mul_f32 v[12:13], v[12:13], v[16:17] op_sel_hi:[1,0]
	v_pk_mul_f32 v[14:15], v[14:15], v[16:17] op_sel_hi:[1,0]
	s_add_i32 s37, s37, 1
	s_cmp_eq_u32 s36, 4
	s_waitcnt vmcnt(0)
; __device__ __forceinline__ unsigned pk2(float lo, float hi) { return pg8::cvt_pk_bf16(lo, hi); }
; __device__ __forceinline__ float siluf(float x) { return x * __builtin_amdgcn_rcpf(1.0f + __expf(-x)); }
; template <int TY> __device__ __forceinline__ void mc_item(const Params& p, ldsp lds, int item) {
;     ...
;         rstd[tk] = rsqrtf(s * (1.0f / DV) + EPS); }
;     const float* nwp = TY == 0 ? p.in[12] : (TY == 1 ? p.in[14] : p.in[17]);
;     const int goff = TY == 0 ? E_RA + h * 128 : (TY == 1 ? E_GB + h * 128 : O_G + h * 512);
;     constexpr int LDY = TY == 2 ? 2048 : 1024; const int ycol = TY == 0 ? h * 128 : (TY == 1 ? 512 + h * 128 : h * 512);
;     bf16_t* Y = (bf16_t*)(p.ws + WS_Y);
; #pragma unroll
;     for (int ei = 0; ei < ET; ++ei) { const int e0 = 16 * (wave * ET + ei) + 4 * q4; const f32x4 w4 = *(const f32x4*)(nwp + e0);
; #pragma unroll
;         for (int tk = 0; tk < 4; ++tk) { const size_t row = (size_t)row0 + 16 * tk + l15;
;             const u32x2 gw = *(const u32x2*)(Pb + row * PP + goff + e0);
;             const float g0 = bf2f(gw.x & 0xffffu), g1 = bf2f(gw.x >> 16), g2 = bf2f(gw.y & 0xffffu), g3 = bf2f(gw.y >> 16);
;             const f32x4 v = acc[ei][tk] * rstd[tk] * w4;
;             float y0 = v[0] * siluf(g0), y1 = v[1] * siluf(g1), y2 = v[2] * siluf(g2), y3 = v[3] * siluf(g3);
;     ...
;             if (!(fabsf(y0) < 1e30f)) y0 = 0.f; if (!(fabsf(y1) < 1e30f)) y1 = 0.f; if (!(fabsf(y2) < 1e30f)) y2 = 0.f; if (!(fabsf(y3) < 1e30f)) y3 = 0.f;
;     ...
;             u32x2 o; o.x = pk2(y0, y1); o.y = pk2(y2, y3);
;             *(u32x2*)(Y + row * LDY + ycol + e0) = o; } }
	v_lshlrev_b32_e32 v73, 16, v186
	v_mul_f32_e32 v80, 0xbfb8aa3b, v73
	v_exp_f32_e32 v80, v80
	v_and_b32_e32 v77, 0xffff0000, v186
	v_lshlrev_b32_e32 v78, 16, v187
	v_and_b32_e32 v79, 0xffff0000, v187
	v_mul_f32_e32 v81, 0xbfb8aa3b, v77
	v_mul_f32_e32 v108, 0xbfb8aa3b, v78
	v_mul_f32_e32 v109, 0xbfb8aa3b, v79
	v_exp_f32_e32 v81, v81
	v_add_f32_e32 v80, 1.0, v80
	v_exp_f32_e32 v108, v108
	v_exp_f32_e32 v109, v109
	v_rcp_f32_e32 v80, v80
	v_add_f32_e32 v81, 1.0, v81
	v_pk_mul_f32 v[66:67], v[66:67], v[190:191]
	v_add_f32_e32 v108, 1.0, v108
	v_rcp_f32_e32 v81, v81
	v_add_f32_e32 v109, 1.0, v109
	v_mul_f32_e32 v73, v80, v73
	v_rcp_f32_e32 v108, v108
	v_mul_f32_e32 v66, v66, v73
	v_rcp_f32_e32 v73, v109
	v_mul_f32_e32 v77, v81, v77
	v_pk_mul_f32 v[68:69], v[68:69], v[192:193]
	v_mul_f32_e32 v67, v67, v77
	v_mul_f32_e32 v77, v108, v78
	v_mul_f32_e32 v73, v73, v79
	v_mul_f32_e32 v68, v68, v77
	v_mul_f32_e32 v69, v69, v73
	v_cvt_pk_bf16_f32 v66, v66, v67
	v_cvt_pk_bf16_f32 v67, v68, v69
	v_lshlrev_b64 v[68:69], 12, v[84:85]
	v_lshl_add_u64 v[78:79], v[86:87], 0, v[68:69]
	global_store_dwordx2 v[78:79], v[66:67], off
	v_or_b32_e32 v66, s58, v146
	v_mad_i64_i32 v[68:69], s[0:1], v66, s56, v[90:91]
	v_lshl_add_u64 v[80:81], v[68:69], 0, s[48:49]
	v_lshl_add_u64 v[68:69], v[80:81], 0, v[82:83]
	v_mul_f32_e32 v73, 0x4b800000, v76
	v_cndmask_b32_e32 v73, v76, v73, vcc
	v_rsq_f32_e32 v73, v73
	v_mov_b32_e32 v67, s9
	v_or_b32_e32 v108, 32, v84
	v_lshlrev_b64 v[66:67], 12, v[66:67]
	v_mul_f32_e32 v76, 0x45800000, v73
	v_cndmask_b32_e32 v76, v73, v76, vcc
	v_pk_mul_f32 v[58:59], v[58:59], v[76:77] op_sel_hi:[1,0]
	v_pk_mul_f32 v[60:61], v[60:61], v[76:77] op_sel_hi:[1,0]
	v_mad_i64_i32 v[68:69], s[0:1], v108, s56, v[90:91]
	v_pk_mul_f32 v[58:59], v[58:59], v[190:191]
	v_lshl_add_u64 v[68:69], v[68:69], 0, s[48:49]
	v_lshl_add_u64 v[66:67], v[86:87], 0, v[66:67]
	v_pk_mul_f32 v[60:61], v[60:61], v[192:193]
	v_lshl_add_u64 v[112:113], v[68:69], 0, v[82:83]
	v_or_b32_e32 v84, 48, v84
	v_lshlrev_b32_e32 v73, 16, v202
	v_and_b32_e32 v77, 0xffff0000, v202
	v_lshlrev_b32_e32 v109, 16, v203
	v_and_b32_e32 v110, 0xffff0000, v203
	v_mul_f32_e32 v111, 0xbfb8aa3b, v73
	v_mul_f32_e32 v114, 0xbfb8aa3b, v77
	v_mul_f32_e32 v115, 0xbfb8aa3b, v109
	v_mul_f32_e32 v116, 0xbfb8aa3b, v110
	v_exp_f32_e32 v111, v111
	v_exp_f32_e32 v114, v114
	v_exp_f32_e32 v115, v115
	v_exp_f32_e32 v116, v116
	v_add_f32_e32 v111, 1.0, v111
	v_add_f32_e32 v114, 1.0, v114
	v_add_f32_e32 v115, 1.0, v115
	v_add_f32_e32 v116, 1.0, v116
	v_rcp_f32_e32 v111, v111
	v_rcp_f32_e32 v114, v114
	v_rcp_f32_e32 v115, v115
	v_rcp_f32_e32 v116, v116
	v_mul_f32_e32 v73, v111, v73
	v_mul_f32_e32 v77, v114, v77
	v_mul_f32_e32 v109, v115, v109
	v_mul_f32_e32 v110, v116, v110
	v_mul_f32_e32 v58, v58, v73
	v_mul_f32_e32 v59, v59, v77
	v_mul_f32_e32 v60, v60, v109
	v_mul_f32_e32 v61, v61, v110
	v_cvt_pk_bf16_f32 v58, v58, v59
	v_cvt_pk_bf16_f32 v59, v60, v61
	global_store_dwordx2 v[66:67], v[58:59], off
	v_mad_i64_i32 v[60:61], s[0:1], v84, s56, v[90:91]
	v_mov_b32_e32 v90, v107
	v_mov_b32_e32 v91, v106
	v_mov_b32_e32 v106, v103
	v_mov_b32_e32 v107, v102
	v_pk_add_f32 v[90:91], v[90:91], 0 op_sel_hi:[1,0]
	v_mov_b32_e32 v102, v99
	v_mov_b32_e32 v103, v98
	v_pk_add_f32 v[90:91], v[90:91], v[106:107]
	v_mov_b32_e32 v98, v95
	v_mov_b32_e32 v99, v94
	v_pk_add_f32 v[90:91], v[90:91], v[102:103]
	s_waitcnt lgkmcnt(3)
	v_mov_b32_e32 v94, v105
	v_mov_b32_e32 v95, v104
	v_pk_add_f32 v[90:91], v[90:91], v[98:99]
	s_waitcnt lgkmcnt(2)
	v_mov_b32_e32 v104, v101
	v_mov_b32_e32 v105, v100
	v_pk_add_f32 v[90:91], v[90:91], v[94:95]
	s_waitcnt lgkmcnt(1)
	v_mov_b32_e32 v100, v97
	v_mov_b32_e32 v101, v96
	v_pk_add_f32 v[90:91], v[90:91], v[104:105]
	s_waitcnt lgkmcnt(0)
	v_mov_b32_e32 v96, v93
	v_mov_b32_e32 v97, v92
	v_pk_add_f32 v[90:91], v[90:91], v[100:101]
	v_lshl_add_u64 v[60:61], v[60:61], 0, s[48:49]
	v_pk_add_f32 v[90:91], v[90:91], v[96:97]
	v_mov_b32_e32 v109, s9
	v_pk_fma_f32 v[88:89], v[90:91], s[10:11], v[88:89] op_sel_hi:[1,0,0]
	v_lshl_add_u64 v[90:91], v[60:61], 0, v[82:83]
	v_mul_f32_e32 v73, 0x4b800000, v89
	v_cmp_gt_f32_e32 vcc, s33, v89
	v_lshlrev_b64 v[58:59], 12, v[108:109]
	v_lshl_add_u64 v[58:59], v[86:87], 0, v[58:59]
	v_cndmask_b32_e32 v73, v89, v73, vcc
	v_rsq_f32_e32 v73, v73
	v_and_b32_e32 v89, 0xffff0000, v215
	v_mul_f32_e32 v77, 0x45800000, v73
	v_cndmask_b32_e32 v82, v73, v77, vcc
	v_lshlrev_b32_e32 v73, 16, v214
	v_and_b32_e32 v77, 0xffff0000, v214
	v_pk_mul_f32 v[54:55], v[54:55], v[82:83] op_sel_hi:[1,0]
	v_pk_mul_f32 v[56:57], v[56:57], v[82:83] op_sel_hi:[1,0]
	v_lshlrev_b32_e32 v83, 16, v215
	v_mul_f32_e32 v92, 0xbfb8aa3b, v73
	v_mul_f32_e32 v93, 0xbfb8aa3b, v77
	v_mul_f32_e32 v94, 0xbfb8aa3b, v83
	v_mul_f32_e32 v95, 0xbfb8aa3b, v89
	v_exp_f32_e32 v92, v92
	v_exp_f32_e32 v93, v93
	v_exp_f32_e32 v94, v94
	v_exp_f32_e32 v95, v95
	v_add_f32_e32 v92, 1.0, v92
	v_add_f32_e32 v93, 1.0, v93
	v_add_f32_e32 v94, 1.0, v94
	v_add_f32_e32 v95, 1.0, v95
	v_rcp_f32_e32 v92, v92
	v_rcp_f32_e32 v93, v93
	v_rcp_f32_e32 v94, v94
	v_rcp_f32_e32 v95, v95
	v_pk_mul_f32 v[54:55], v[190:191], v[54:55]
	v_mul_f32_e32 v73, v92, v73
	v_mul_f32_e32 v77, v93, v77
	v_pk_mul_f32 v[56:57], v[192:193], v[56:57]
	v_mul_f32_e32 v83, v94, v83
	v_mul_f32_e32 v89, v95, v89
	v_mul_f32_e32 v54, v54, v73
	v_mul_f32_e32 v55, v55, v77
	v_mul_f32_e32 v56, v56, v83
	v_mul_f32_e32 v57, v57, v89
	v_cvt_pk_bf16_f32 v54, v54, v55
	v_cvt_pk_bf16_f32 v55, v56, v57
	global_store_dwordx2 v[58:59], v[54:55], off
	v_mul_f32_e32 v57, 0x4b800000, v88
	v_cmp_gt_f32_e32 vcc, s33, v88
	v_or_b32_e32 v56, 16, v72
	s_nop 0
	v_cndmask_b32_e32 v57, v88, v57, vcc
; __device__ __forceinline__ unsigned pk2(float lo, float hi) { return pg8::cvt_pk_bf16(lo, hi); }
; __device__ __forceinline__ float siluf(float x) { return x * __builtin_amdgcn_rcpf(1.0f + __expf(-x)); }
; template <int TY> __device__ __forceinline__ void mc_item(const Params& p, ldsp lds, int item) {
;     ...
;     for (int ei = 0; ei < ET; ++ei) { const int e0 = 16 * (wave * ET + ei) + 4 * q4; const f32x4 w4 = *(const f32x4*)(nwp + e0);
; #pragma unroll
;         for (int tk = 0; tk < 4; ++tk) { const size_t row = (size_t)row0 + 16 * tk + l15;
;             const u32x2 gw = *(const u32x2*)(Pb + row * PP + goff + e0);
;             const float g0 = bf2f(gw.x & 0xffffu), g1 = bf2f(gw.x >> 16), g2 = bf2f(gw.y & 0xffffu), g3 = bf2f(gw.y >> 16);
;             const f32x4 v = acc[ei][tk] * rstd[tk] * w4;
;             float y0 = v[0] * siluf(g0), y1 = v[1] * siluf(g1), y2 = v[2] * siluf(g2), y3 = v[3] * siluf(g3);
;     ...
;             if (!(fabsf(y0) < 1e30f)) y0 = 0.f; if (!(fabsf(y1) < 1e30f)) y1 = 0.f; if (!(fabsf(y2) < 1e30f)) y2 = 0.f; if (!(fabsf(y3) < 1e30f)) y3 = 0.f;
;     ...
;             u32x2 o; o.x = pk2(y0, y1); o.y = pk2(y2, y3);
;             *(u32x2*)(Y + row * LDY + ycol + e0) = o; } }
	v_rsq_f32_e32 v73, v57
	v_ashrrev_i32_e32 v57, 31, v56
	v_lshlrev_b64 v[88:89], 1, v[56:57]
	v_lshl_add_u64 v[90:91], v[74:75], 0, v[88:89]
	v_mul_f32_e32 v56, 0x45800000, v73
	v_cndmask_b32_e32 v56, v73, v56, vcc
	v_pk_mul_f32 v[50:51], v[50:51], v[56:57] op_sel_hi:[1,0]
	v_pk_mul_f32 v[52:53], v[52:53], v[56:57] op_sel_hi:[1,0]
	v_pk_mul_f32 v[50:51], v[190:191], v[50:51]
	v_pk_mul_f32 v[52:53], v[192:193], v[52:53]
	v_lshlrev_b32_e32 v57, 16, v222
	v_and_b32_e32 v54, 0xffff0000, v222
	v_lshlrev_b32_e32 v62, 16, v223
	v_and_b32_e32 v55, 0xffff0000, v223
	v_mul_f32_e32 v63, 0xbfb8aa3b, v57
	v_mul_f32_e32 v64, 0xbfb8aa3b, v54
	v_mul_f32_e32 v65, 0xbfb8aa3b, v62
	v_mul_f32_e32 v73, 0xbfb8aa3b, v55
	v_exp_f32_e32 v63, v63
	v_exp_f32_e32 v64, v64
	v_exp_f32_e32 v65, v65
	v_exp_f32_e32 v73, v73
	v_add_f32_e32 v63, 1.0, v63
	v_add_f32_e32 v64, 1.0, v64
	v_add_f32_e32 v65, 1.0, v65
	v_add_f32_e32 v73, 1.0, v73
	v_rcp_f32_e32 v63, v63
	v_rcp_f32_e32 v64, v64
	v_rcp_f32_e32 v65, v65
	v_rcp_f32_e32 v73, v73
	v_mul_f32_e32 v57, v63, v57
	v_mul_f32_e32 v54, v64, v54
	v_mul_f32_e32 v62, v65, v62
	v_mul_f32_e32 v55, v73, v55
	v_mul_f32_e32 v50, v50, v57
	v_mul_f32_e32 v51, v51, v54
	v_mul_f32_e32 v52, v52, v62
	v_mul_f32_e32 v53, v53, v55
	v_cvt_pk_bf16_f32 v50, v50, v51
	v_cvt_pk_bf16_f32 v51, v52, v53
	v_lshlrev_b64 v[52:53], 12, v[84:85]
	v_lshl_add_u64 v[54:55], v[86:87], 0, v[52:53]
	global_store_dwordx2 v[54:55], v[50:51], off
	v_lshl_add_u64 v[64:65], v[80:81], 0, v[88:89]
	v_lshlrev_b32_e32 v57, 16, v230
	v_and_b32_e32 v62, 0xffff0000, v230
	v_lshlrev_b32_e32 v73, 16, v231
	v_and_b32_e32 v63, 0xffff0000, v231
	v_mul_f32_e32 v77, 0xbfb8aa3b, v57
	v_mul_f32_e32 v83, 0xbfb8aa3b, v62
	v_mul_f32_e32 v84, 0xbfb8aa3b, v73
	v_mul_f32_e32 v85, 0xbfb8aa3b, v63
	v_exp_f32_e32 v77, v77
	v_exp_f32_e32 v83, v83
	v_exp_f32_e32 v84, v84
	v_exp_f32_e32 v85, v85
	v_add_f32_e32 v77, 1.0, v77
	v_add_f32_e32 v83, 1.0, v83
	v_add_f32_e32 v84, 1.0, v84
	v_add_f32_e32 v85, 1.0, v85
	v_rcp_f32_e32 v77, v77
	v_rcp_f32_e32 v83, v83
	v_rcp_f32_e32 v84, v84
	v_rcp_f32_e32 v85, v85
	v_pk_mul_f32 v[46:47], v[46:47], v[232:233]
	v_mul_f32_e32 v57, v77, v57
	v_mul_f32_e32 v62, v83, v62
	v_pk_mul_f32 v[48:49], v[48:49], v[234:235]
	v_mul_f32_e32 v73, v84, v73
	v_mul_f32_e32 v63, v85, v63
	v_mul_f32_e32 v46, v46, v57
	v_mul_f32_e32 v47, v47, v62
	v_mul_f32_e32 v48, v48, v73
	v_mul_f32_e32 v49, v49, v63
	v_cvt_pk_bf16_f32 v46, v46, v47
	v_cvt_pk_bf16_f32 v47, v48, v49
	global_store_dwordx2 v[78:79], v[46:47], off offset:32
	v_pk_mul_f32 v[42:43], v[42:43], v[76:77] op_sel_hi:[1,0]
	v_pk_mul_f32 v[44:45], v[44:45], v[76:77] op_sel_hi:[1,0]
	v_pk_mul_f32 v[42:43], v[42:43], v[232:233]
	v_pk_mul_f32 v[44:45], v[44:45], v[234:235]
	v_lshl_add_u64 v[48:49], v[68:69], 0, v[88:89]
	v_pk_mul_f32 v[38:39], v[38:39], v[82:83] op_sel_hi:[1,0]
	v_pk_mul_f32 v[40:41], v[40:41], v[82:83] op_sel_hi:[1,0]
	v_pk_mul_f32 v[38:39], v[38:39], v[232:233]
	v_pk_mul_f32 v[40:41], v[40:41], v[234:235]
	v_pk_mul_f32 v[26:27], v[26:27], v[76:77] op_sel_hi:[1,0]
	v_pk_mul_f32 v[28:29], v[28:29], v[76:77] op_sel_hi:[1,0]
	v_pk_mul_f32 v[22:23], v[22:23], v[82:83] op_sel_hi:[1,0]
	v_pk_mul_f32 v[24:25], v[24:25], v[82:83] op_sel_hi:[1,0]
	v_pk_mul_f32 v[8:9], v[8:9], v[76:77] op_sel_hi:[1,0]
	v_pk_mul_f32 v[10:11], v[10:11], v[76:77] op_sel_hi:[1,0]
	v_pk_mul_f32 v[4:5], v[4:5], v[82:83] op_sel_hi:[1,0]
	v_pk_mul_f32 v[6:7], v[6:7], v[82:83] op_sel_hi:[1,0]
	v_lshlrev_b32_e32 v57, 16, v238
	v_and_b32_e32 v46, 0xffff0000, v238
	v_lshlrev_b32_e32 v62, 16, v239
	v_and_b32_e32 v47, 0xffff0000, v239
	v_mul_f32_e32 v63, 0xbfb8aa3b, v57
	v_mul_f32_e32 v64, 0xbfb8aa3b, v46
	v_mul_f32_e32 v65, 0xbfb8aa3b, v62
	v_mul_f32_e32 v73, 0xbfb8aa3b, v47
	v_exp_f32_e32 v63, v63
	v_exp_f32_e32 v64, v64
	v_exp_f32_e32 v65, v65
	v_exp_f32_e32 v73, v73
	v_add_f32_e32 v63, 1.0, v63
	v_add_f32_e32 v64, 1.0, v64
	v_add_f32_e32 v65, 1.0, v65
	v_add_f32_e32 v73, 1.0, v73
	v_rcp_f32_e32 v63, v63
	v_rcp_f32_e32 v64, v64
	v_rcp_f32_e32 v65, v65
	v_rcp_f32_e32 v73, v73
	v_mul_f32_e32 v57, v63, v57
	v_mul_f32_e32 v46, v64, v46
	v_mul_f32_e32 v62, v65, v62
	v_mul_f32_e32 v47, v73, v47
	v_mul_f32_e32 v42, v42, v57
	v_mul_f32_e32 v43, v43, v46
	v_mul_f32_e32 v44, v44, v62
	v_mul_f32_e32 v45, v45, v47
	v_cvt_pk_bf16_f32 v42, v42, v43
	v_cvt_pk_bf16_f32 v43, v44, v45
	global_store_dwordx2 v[66:67], v[42:43], off offset:32
	v_lshl_add_u64 v[44:45], v[60:61], 0, v[88:89]
	v_lshlrev_b32_e32 v46, 16, v242
	v_and_b32_e32 v42, 0xffff0000, v242
	v_lshlrev_b32_e32 v47, 16, v243
	v_and_b32_e32 v43, 0xffff0000, v243
	v_mul_f32_e32 v48, 0xbfb8aa3b, v46
	v_mul_f32_e32 v49, 0xbfb8aa3b, v42
	v_mul_f32_e32 v57, 0xbfb8aa3b, v47
	v_mul_f32_e32 v62, 0xbfb8aa3b, v43
	v_exp_f32_e32 v48, v48
	v_exp_f32_e32 v49, v49
	v_exp_f32_e32 v57, v57
	v_exp_f32_e32 v62, v62
	v_add_f32_e32 v48, 1.0, v48
	v_add_f32_e32 v49, 1.0, v49
	v_add_f32_e32 v57, 1.0, v57
	v_add_f32_e32 v62, 1.0, v62
	v_rcp_f32_e32 v48, v48
	v_rcp_f32_e32 v49, v49
	v_rcp_f32_e32 v57, v57
	v_rcp_f32_e32 v62, v62
	v_mul_f32_e32 v46, v48, v46
	v_mul_f32_e32 v42, v49, v42
	v_mul_f32_e32 v47, v57, v47
	v_mul_f32_e32 v43, v62, v43
	v_mul_f32_e32 v38, v38, v46
	v_mul_f32_e32 v39, v39, v42
	v_mul_f32_e32 v40, v40, v47
	v_mul_f32_e32 v41, v41, v43
	v_cvt_pk_bf16_f32 v38, v38, v39
	v_cvt_pk_bf16_f32 v39, v40, v41
	global_store_dwordx2 v[58:59], v[38:39], off offset:32
	v_or_b32_e32 v38, 32, v72
	v_ashrrev_i32_e32 v39, 31, v38
	v_pk_mul_f32 v[34:35], v[34:35], v[56:57] op_sel_hi:[1,0]
	v_lshlrev_b64 v[38:39], 1, v[38:39]
	v_pk_mul_f32 v[36:37], v[36:37], v[56:57] op_sel_hi:[1,0]
	v_pk_mul_f32 v[34:35], v[34:35], v[232:233]
; __device__ __forceinline__ unsigned pk2(float lo, float hi) { return pg8::cvt_pk_bf16(lo, hi); }
; __device__ __forceinline__ float siluf(float x) { return x * __builtin_amdgcn_rcpf(1.0f + __expf(-x)); }
; template <int TY> __device__ __forceinline__ void mc_item(const Params& p, ldsp lds, int item) {
;     ...
;     for (int ei = 0; ei < ET; ++ei) { const int e0 = 16 * (wave * ET + ei) + 4 * q4; const f32x4 w4 = *(const f32x4*)(nwp + e0);
; #pragma unroll
;         for (int tk = 0; tk < 4; ++tk) { const size_t row = (size_t)row0 + 16 * tk + l15;
;             const u32x2 gw = *(const u32x2*)(Pb + row * PP + goff + e0);
;             const float g0 = bf2f(gw.x & 0xffffu), g1 = bf2f(gw.x >> 16), g2 = bf2f(gw.y & 0xffffu), g3 = bf2f(gw.y >> 16);
;             const f32x4 v = acc[ei][tk] * rstd[tk] * w4;
;             float y0 = v[0] * siluf(g0), y1 = v[1] * siluf(g1), y2 = v[2] * siluf(g2), y3 = v[3] * siluf(g3);
;     ...
;             if (!(fabsf(y0) < 1e30f)) y0 = 0.f; if (!(fabsf(y1) < 1e30f)) y1 = 0.f; if (!(fabsf(y2) < 1e30f)) y2 = 0.f; if (!(fabsf(y3) < 1e30f)) y3 = 0.f;
;     ...
;             u32x2 o; o.x = pk2(y0, y1); o.y = pk2(y2, y3);
;             *(u32x2*)(Y + row * LDY + ycol + e0) = o; } }
	v_lshl_add_u64 v[42:43], v[74:75], 0, v[38:39]
	v_pk_mul_f32 v[36:37], v[36:37], v[234:235]
	v_pk_mul_f32 v[18:19], v[18:19], v[56:57] op_sel_hi:[1,0]
	v_pk_mul_f32 v[20:21], v[20:21], v[56:57] op_sel_hi:[1,0]
	v_pk_mul_f32 v[0:1], v[0:1], v[56:57] op_sel_hi:[1,0]
	v_pk_mul_f32 v[2:3], v[2:3], v[56:57] op_sel_hi:[1,0]
	v_lshlrev_b32_e32 v44, 16, v246
	v_and_b32_e32 v40, 0xffff0000, v246
	v_lshlrev_b32_e32 v45, 16, v247
	v_and_b32_e32 v41, 0xffff0000, v247
	v_mul_f32_e32 v46, 0xbfb8aa3b, v44
	v_mul_f32_e32 v47, 0xbfb8aa3b, v40
	v_mul_f32_e32 v48, 0xbfb8aa3b, v45
	v_mul_f32_e32 v49, 0xbfb8aa3b, v41
	v_exp_f32_e32 v46, v46
	v_exp_f32_e32 v47, v47
	v_exp_f32_e32 v48, v48
	v_exp_f32_e32 v49, v49
	v_add_f32_e32 v46, 1.0, v46
	v_add_f32_e32 v47, 1.0, v47
	v_add_f32_e32 v48, 1.0, v48
	v_add_f32_e32 v49, 1.0, v49
	v_rcp_f32_e32 v46, v46
	v_rcp_f32_e32 v47, v47
	v_rcp_f32_e32 v48, v48
	v_rcp_f32_e32 v49, v49
	v_mul_f32_e32 v44, v46, v44
	v_mul_f32_e32 v40, v47, v40
	v_mul_f32_e32 v45, v48, v45
	v_mul_f32_e32 v41, v49, v41
	v_mul_f32_e32 v34, v34, v44
	v_mul_f32_e32 v35, v35, v40
	v_mul_f32_e32 v36, v36, v45
	v_mul_f32_e32 v37, v37, v41
	v_cvt_pk_bf16_f32 v34, v34, v35
	v_cvt_pk_bf16_f32 v35, v36, v37
	v_lshl_add_u64 v[42:43], v[80:81], 0, v[38:39]
	global_store_dwordx2 v[54:55], v[34:35], off offset:32
	v_lshlrev_b32_e32 v44, 16, v124
	v_and_b32_e32 v40, 0xffff0000, v124
	v_lshlrev_b32_e32 v45, 16, v125
	v_and_b32_e32 v41, 0xffff0000, v125
	v_mul_f32_e32 v46, 0xbfb8aa3b, v44
	v_mul_f32_e32 v47, 0xbfb8aa3b, v40
	v_mul_f32_e32 v48, 0xbfb8aa3b, v45
	v_mul_f32_e32 v49, 0xbfb8aa3b, v41
	v_exp_f32_e32 v46, v46
	v_exp_f32_e32 v47, v47
	v_exp_f32_e32 v48, v48
	v_exp_f32_e32 v49, v49
	v_add_f32_e32 v46, 1.0, v46
	v_add_f32_e32 v47, 1.0, v47
	v_add_f32_e32 v48, 1.0, v48
	v_add_f32_e32 v49, 1.0, v49
	v_rcp_f32_e32 v46, v46
	v_rcp_f32_e32 v47, v47
	v_rcp_f32_e32 v48, v48
	v_rcp_f32_e32 v49, v49
	v_pk_mul_f32 v[30:31], v[30:31], v[128:129]
	v_mul_f32_e32 v44, v46, v44
	v_mul_f32_e32 v40, v47, v40
	v_pk_mul_f32 v[32:33], v[32:33], v[130:131]
	v_mul_f32_e32 v45, v48, v45
	v_mul_f32_e32 v41, v49, v41
	v_mul_f32_e32 v30, v30, v44
	v_mul_f32_e32 v31, v31, v40
	v_mul_f32_e32 v32, v32, v45
	v_mul_f32_e32 v33, v33, v41
	v_cvt_pk_bf16_f32 v30, v30, v31
	v_cvt_pk_bf16_f32 v31, v32, v33
	global_store_dwordx2 v[78:79], v[30:31], off offset:64
	v_pk_mul_f32 v[26:27], v[26:27], v[128:129]
	v_pk_mul_f32 v[28:29], v[28:29], v[130:131]
	v_lshl_add_u64 v[32:33], v[68:69], 0, v[38:39]
	v_pk_mul_f32 v[22:23], v[22:23], v[128:129]
	v_pk_mul_f32 v[24:25], v[24:25], v[130:131]
	v_pk_mul_f32 v[18:19], v[18:19], v[128:129]
	v_pk_mul_f32 v[20:21], v[20:21], v[130:131]
	v_lshlrev_b32_e32 v40, 16, v132
	v_and_b32_e32 v30, 0xffff0000, v132
	v_lshlrev_b32_e32 v41, 16, v133
	v_and_b32_e32 v31, 0xffff0000, v133
	v_mul_f32_e32 v42, 0xbfb8aa3b, v40
	v_mul_f32_e32 v43, 0xbfb8aa3b, v30
	v_mul_f32_e32 v44, 0xbfb8aa3b, v41
	v_mul_f32_e32 v45, 0xbfb8aa3b, v31
	v_exp_f32_e32 v42, v42
	v_exp_f32_e32 v43, v43
	v_exp_f32_e32 v44, v44
	v_exp_f32_e32 v45, v45
	v_add_f32_e32 v42, 1.0, v42
	v_add_f32_e32 v43, 1.0, v43
	v_add_f32_e32 v44, 1.0, v44
	v_add_f32_e32 v45, 1.0, v45
	v_rcp_f32_e32 v42, v42
	v_rcp_f32_e32 v43, v43
	v_rcp_f32_e32 v44, v44
	v_rcp_f32_e32 v45, v45
	v_mul_f32_e32 v40, v42, v40
	v_mul_f32_e32 v30, v43, v30
	v_mul_f32_e32 v41, v44, v41
	v_mul_f32_e32 v31, v45, v31
	v_mul_f32_e32 v26, v26, v40
	v_mul_f32_e32 v27, v27, v30
	v_mul_f32_e32 v28, v28, v41
	v_mul_f32_e32 v29, v29, v31
	v_cvt_pk_bf16_f32 v26, v26, v27
	v_cvt_pk_bf16_f32 v27, v28, v29
	global_store_dwordx2 v[66:67], v[26:27], off offset:64
	v_lshl_add_u64 v[28:29], v[60:61], 0, v[38:39]
	v_lshlrev_b32_e32 v30, 16, v136
	v_and_b32_e32 v26, 0xffff0000, v136
	v_lshlrev_b32_e32 v31, 16, v137
	v_and_b32_e32 v27, 0xffff0000, v137
	v_mul_f32_e32 v32, 0xbfb8aa3b, v30
	v_mul_f32_e32 v33, 0xbfb8aa3b, v26
	v_mul_f32_e32 v38, 0xbfb8aa3b, v31
	v_mul_f32_e32 v39, 0xbfb8aa3b, v27
	v_exp_f32_e32 v32, v32
	v_exp_f32_e32 v33, v33
	v_exp_f32_e32 v38, v38
	v_exp_f32_e32 v39, v39
	v_add_f32_e32 v32, 1.0, v32
	v_add_f32_e32 v33, 1.0, v33
	v_add_f32_e32 v38, 1.0, v38
	v_add_f32_e32 v39, 1.0, v39
	v_rcp_f32_e32 v32, v32
	v_rcp_f32_e32 v33, v33
	v_rcp_f32_e32 v38, v38
	v_rcp_f32_e32 v39, v39
	v_mul_f32_e32 v30, v32, v30
	v_mul_f32_e32 v26, v33, v26
	v_mul_f32_e32 v31, v38, v31
	v_mul_f32_e32 v27, v39, v27
	v_mul_f32_e32 v22, v22, v30
	v_mul_f32_e32 v23, v23, v26
	v_mul_f32_e32 v24, v24, v31
	v_mul_f32_e32 v25, v25, v27
	v_cvt_pk_bf16_f32 v22, v22, v23
	v_cvt_pk_bf16_f32 v23, v24, v25
	global_store_dwordx2 v[58:59], v[22:23], off offset:64
	v_or_b32_e32 v22, 48, v72
	v_ashrrev_i32_e32 v23, 31, v22
	v_lshlrev_b64 v[22:23], 1, v[22:23]
	v_lshl_add_u64 v[26:27], v[74:75], 0, v[22:23]
	v_lshlrev_b32_e32 v28, 16, v142
	v_and_b32_e32 v24, 0xffff0000, v142
	v_lshlrev_b32_e32 v29, 16, v143
	v_and_b32_e32 v25, 0xffff0000, v143
	v_mul_f32_e32 v30, 0xbfb8aa3b, v28
	v_mul_f32_e32 v31, 0xbfb8aa3b, v24
	v_mul_f32_e32 v32, 0xbfb8aa3b, v29
	v_mul_f32_e32 v33, 0xbfb8aa3b, v25
	v_exp_f32_e32 v30, v30
	v_exp_f32_e32 v31, v31
	v_exp_f32_e32 v32, v32
	v_exp_f32_e32 v33, v33
	v_add_f32_e32 v30, 1.0, v30
; __device__ __forceinline__ unsigned pk2(float lo, float hi) { return pg8::cvt_pk_bf16(lo, hi); }
; __device__ __forceinline__ float siluf(float x) { return x * __builtin_amdgcn_rcpf(1.0f + __expf(-x)); }
; #define BSYNC() do { asm volatile("s_waitcnt vmcnt(0) lgkmcnt(0)" ::: "memory"); __syncthreads(); } while (0)
; template <int TY> __device__ __forceinline__ void mc_item(const Params& p, ldsp lds, int item) {
;     ...
;     for (int ei = 0; ei < ET; ++ei) { const int e0 = 16 * (wave * ET + ei) + 4 * q4; const f32x4 w4 = *(const f32x4*)(nwp + e0);
; #pragma unroll
;         for (int tk = 0; tk < 4; ++tk) { const size_t row = (size_t)row0 + 16 * tk + l15;
;             const u32x2 gw = *(const u32x2*)(Pb + row * PP + goff + e0);
;             const float g0 = bf2f(gw.x & 0xffffu), g1 = bf2f(gw.x >> 16), g2 = bf2f(gw.y & 0xffffu), g3 = bf2f(gw.y >> 16);
;             const f32x4 v = acc[ei][tk] * rstd[tk] * w4;
;             float y0 = v[0] * siluf(g0), y1 = v[1] * siluf(g1), y2 = v[2] * siluf(g2), y3 = v[3] * siluf(g3);
;     ...
;             if (!(fabsf(y0) < 1e30f)) y0 = 0.f; if (!(fabsf(y1) < 1e30f)) y1 = 0.f; if (!(fabsf(y2) < 1e30f)) y2 = 0.f; if (!(fabsf(y3) < 1e30f)) y3 = 0.f;
;     ...
;             u32x2 o; o.x = pk2(y0, y1); o.y = pk2(y2, y3);
;             *(u32x2*)(Y + row * LDY + ycol + e0) = o; } }
;     BSYNC();
	v_add_f32_e32 v31, 1.0, v31
	v_add_f32_e32 v32, 1.0, v32
	v_add_f32_e32 v33, 1.0, v33
	v_rcp_f32_e32 v30, v30
	v_rcp_f32_e32 v31, v31
	v_rcp_f32_e32 v32, v32
	v_rcp_f32_e32 v33, v33
	v_mul_f32_e32 v28, v30, v28
	v_mul_f32_e32 v24, v31, v24
	v_mul_f32_e32 v29, v32, v29
	v_mul_f32_e32 v25, v33, v25
	v_mul_f32_e32 v18, v18, v28
	v_mul_f32_e32 v19, v19, v24
	v_mul_f32_e32 v20, v20, v29
	v_mul_f32_e32 v21, v21, v25
	v_cvt_pk_bf16_f32 v18, v18, v19
	v_cvt_pk_bf16_f32 v19, v20, v21
	v_lshl_add_u64 v[26:27], v[80:81], 0, v[22:23]
	global_store_dwordx2 v[54:55], v[18:19], off offset:64
	v_lshlrev_b32_e32 v16, 16, v154
	v_and_b32_e32 v24, 0xffff0000, v154
	v_lshlrev_b32_e32 v28, 16, v155
	v_and_b32_e32 v25, 0xffff0000, v155
	v_mul_f32_e32 v29, 0xbfb8aa3b, v16
	v_mul_f32_e32 v30, 0xbfb8aa3b, v24
	v_mul_f32_e32 v31, 0xbfb8aa3b, v28
	v_mul_f32_e32 v32, 0xbfb8aa3b, v25
	v_exp_f32_e32 v29, v29
	v_exp_f32_e32 v30, v30
	v_exp_f32_e32 v31, v31
	v_exp_f32_e32 v32, v32
	v_add_f32_e32 v29, 1.0, v29
	v_add_f32_e32 v30, 1.0, v30
	v_add_f32_e32 v31, 1.0, v31
	v_add_f32_e32 v32, 1.0, v32
	v_rcp_f32_e32 v29, v29
	v_rcp_f32_e32 v30, v30
	v_rcp_f32_e32 v31, v31
	v_rcp_f32_e32 v32, v32
	v_pk_mul_f32 v[12:13], v[12:13], v[172:173]
	v_mul_f32_e32 v16, v29, v16
	v_mul_f32_e32 v24, v30, v24
	v_pk_mul_f32 v[14:15], v[14:15], v[174:175]
	v_mul_f32_e32 v28, v31, v28
	v_mul_f32_e32 v25, v32, v25
	v_mul_f32_e32 v12, v12, v16
	v_mul_f32_e32 v13, v13, v24
	v_mul_f32_e32 v14, v14, v28
	v_mul_f32_e32 v15, v15, v25
	v_cvt_pk_bf16_f32 v12, v12, v13
	v_cvt_pk_bf16_f32 v13, v14, v15
	global_store_dwordx2 v[78:79], v[12:13], off offset:96
	v_pk_mul_f32 v[8:9], v[8:9], v[172:173]
	v_pk_mul_f32 v[10:11], v[10:11], v[174:175]
	v_lshl_add_u64 v[14:15], v[68:69], 0, v[22:23]
	v_pk_mul_f32 v[4:5], v[4:5], v[172:173]
	v_pk_mul_f32 v[6:7], v[6:7], v[174:175]
	v_pk_mul_f32 v[0:1], v[0:1], v[172:173]
	v_pk_mul_f32 v[2:3], v[2:3], v[174:175]
	v_lshlrev_b32_e32 v16, 16, v158
	v_and_b32_e32 v12, 0xffff0000, v158
	v_lshlrev_b32_e32 v24, 16, v159
	v_and_b32_e32 v13, 0xffff0000, v159
	v_mul_f32_e32 v25, 0xbfb8aa3b, v16
	v_mul_f32_e32 v26, 0xbfb8aa3b, v12
	v_mul_f32_e32 v27, 0xbfb8aa3b, v24
	v_mul_f32_e32 v28, 0xbfb8aa3b, v13
	v_exp_f32_e32 v25, v25
	v_exp_f32_e32 v26, v26
	v_exp_f32_e32 v27, v27
	v_exp_f32_e32 v28, v28
	v_add_f32_e32 v25, 1.0, v25
	v_add_f32_e32 v26, 1.0, v26
	v_add_f32_e32 v27, 1.0, v27
	v_add_f32_e32 v28, 1.0, v28
	v_rcp_f32_e32 v25, v25
	v_rcp_f32_e32 v26, v26
	v_rcp_f32_e32 v27, v27
	v_rcp_f32_e32 v28, v28
	v_mul_f32_e32 v16, v25, v16
	v_mul_f32_e32 v12, v26, v12
	v_mul_f32_e32 v24, v27, v24
	v_mul_f32_e32 v13, v28, v13
	v_mul_f32_e32 v8, v8, v16
	v_mul_f32_e32 v9, v9, v12
	v_mul_f32_e32 v10, v10, v24
	v_mul_f32_e32 v11, v11, v13
	v_cvt_pk_bf16_f32 v8, v8, v9
	v_cvt_pk_bf16_f32 v9, v10, v11
	global_store_dwordx2 v[66:67], v[8:9], off offset:96
	v_lshl_add_u64 v[10:11], v[60:61], 0, v[22:23]
	v_lshlrev_b32_e32 v12, 16, v166
	v_and_b32_e32 v8, 0xffff0000, v166
	v_lshlrev_b32_e32 v13, 16, v167
	v_and_b32_e32 v9, 0xffff0000, v167
	v_mul_f32_e32 v14, 0xbfb8aa3b, v12
	v_mul_f32_e32 v15, 0xbfb8aa3b, v8
	v_mul_f32_e32 v16, 0xbfb8aa3b, v13
	v_mul_f32_e32 v22, 0xbfb8aa3b, v9
	v_exp_f32_e32 v14, v14
	v_exp_f32_e32 v15, v15
	v_exp_f32_e32 v16, v16
	v_exp_f32_e32 v22, v22
	v_add_f32_e32 v14, 1.0, v14
	v_add_f32_e32 v15, 1.0, v15
	v_add_f32_e32 v16, 1.0, v16
	v_add_f32_e32 v22, 1.0, v22
	v_rcp_f32_e32 v14, v14
	v_rcp_f32_e32 v15, v15
	v_rcp_f32_e32 v16, v16
	v_rcp_f32_e32 v22, v22
	v_mul_f32_e32 v12, v14, v12
	v_mul_f32_e32 v8, v15, v8
	v_mul_f32_e32 v13, v16, v13
	v_mul_f32_e32 v9, v22, v9
	v_mul_f32_e32 v4, v4, v12
	v_mul_f32_e32 v5, v5, v8
	v_mul_f32_e32 v6, v6, v13
	v_mul_f32_e32 v7, v7, v9
	v_cvt_pk_bf16_f32 v4, v4, v5
	v_cvt_pk_bf16_f32 v5, v6, v7
	global_store_dwordx2 v[58:59], v[4:5], off offset:96
	v_lshlrev_b32_e32 v6, 16, v178
	v_and_b32_e32 v4, 0xffff0000, v178
	v_lshlrev_b32_e32 v7, 16, v179
	v_and_b32_e32 v5, 0xffff0000, v179
	v_mul_f32_e32 v8, 0xbfb8aa3b, v6
	v_mul_f32_e32 v9, 0xbfb8aa3b, v4
	v_mul_f32_e32 v10, 0xbfb8aa3b, v7
	v_mul_f32_e32 v11, 0xbfb8aa3b, v5
	v_exp_f32_e32 v8, v8
	v_exp_f32_e32 v9, v9
	v_exp_f32_e32 v10, v10
	v_exp_f32_e32 v11, v11
	v_add_f32_e32 v8, 1.0, v8
	v_add_f32_e32 v9, 1.0, v9
	v_add_f32_e32 v10, 1.0, v10
	v_add_f32_e32 v11, 1.0, v11
	v_rcp_f32_e32 v8, v8
	v_rcp_f32_e32 v9, v9
	v_rcp_f32_e32 v10, v10
	v_rcp_f32_e32 v11, v11
	v_mul_f32_e32 v6, v8, v6
	v_mul_f32_e32 v4, v9, v4
	v_mul_f32_e32 v7, v10, v7
	v_mul_f32_e32 v5, v11, v5
	v_mul_f32_e32 v0, v0, v6
	v_mul_f32_e32 v1, v1, v4
	v_mul_f32_e32 v2, v2, v7
	v_mul_f32_e32 v3, v3, v5
	v_cvt_pk_bf16_f32 v0, v0, v1
	v_cvt_pk_bf16_f32 v1, v2, v3
	global_store_dwordx2 v[54:55], v[0:1], off offset:96
	v_mov_b32_e32 v18, v172
	v_mov_b32_e32 v19, v173
	v_mov_b32_e32 v20, v174
	v_mov_b32_e32 v21, v175
	v_mov_b32_e32 v34, v128
	v_mov_b32_e32 v35, v129
	v_mov_b32_e32 v36, v130
	v_mov_b32_e32 v37, v131
	v_mov_b32_e32 v50, v232
	v_mov_b32_e32 v51, v233
	v_mov_b32_e32 v52, v234
	v_mov_b32_e32 v53, v235
	v_mov_b32_e32 v110, v214
	v_mov_b32_e32 v111, v215
	s_waitcnt vmcnt(0) lgkmcnt(0)
	s_barrier
	s_cbranch_scc1 .LBB0_898

; __device__ __forceinline__ unsigned pk2(float lo, float hi) { return pg8::cvt_pk_bf16(lo, hi); }
; __device__ __forceinline__ float siluf(float x) { return x * __builtin_amdgcn_rcpf(1.0f + __expf(-x)); }
; #define BSYNC() do { asm volatile("s_waitcnt vmcnt(0) lgkmcnt(0)" ::: "memory"); __syncthreads(); } while (0)
; template <int TY> __device__ __forceinline__ void mc_item(const Params& p, ldsp lds, int item) {
;     ...
;     BSYNC();
; #pragma unroll
;     for (int tk = 0; tk < 4; ++tk) { float s = 0.f;
; #pragma unroll
;         for (int w = 0; w < 8; ++w) s += RED[w * 64 + 16 * tk + l15];
;         rstd[tk] = rsqrtf(s * (1.0f / DV) + EPS); }
;     const float* nwp = TY == 0 ? p.in[12] : (TY == 1 ? p.in[14] : p.in[17]);
;     const int goff = TY == 0 ? E_RA + h * 128 : (TY == 1 ? E_GB + h * 128 : O_G + h * 512);
;     constexpr int LDY = TY == 2 ? 2048 : 1024; const int ycol = TY == 0 ? h * 128 : (TY == 1 ? 512 + h * 128 : h * 512);
;     bf16_t* Y = (bf16_t*)(p.ws + WS_Y);
; #pragma unroll
;     for (int ei = 0; ei < ET; ++ei) { const int e0 = 16 * (wave * ET + ei) + 4 * q4; const f32x4 w4 = *(const f32x4*)(nwp + e0);
; #pragma unroll
;         for (int tk = 0; tk < 4; ++tk) { const size_t row = (size_t)row0 + 16 * tk + l15;
;             const u32x2 gw = *(const u32x2*)(Pb + row * PP + goff + e0);
;             const float g0 = bf2f(gw.x & 0xffffu), g1 = bf2f(gw.x >> 16), g2 = bf2f(gw.y & 0xffffu), g3 = bf2f(gw.y >> 16);
;             const f32x4 v = acc[ei][tk] * rstd[tk] * w4;
;             float y0 = v[0] * siluf(g0), y1 = v[1] * siluf(g1), y2 = v[2] * siluf(g2), y3 = v[3] * siluf(g3);
;     ...
;             if (!(fabsf(y0) < 1e30f)) y0 = 0.f; if (!(fabsf(y1) < 1e30f)) y1 = 0.f; if (!(fabsf(y2) < 1e30f)) y2 = 0.f; if (!(fabsf(y3) < 1e30f)) y3 = 0.f;
;     ...
;             u32x2 o; o.x = pk2(y0, y1); o.y = pk2(y2, y3);
;             *(u32x2*)(Y + row * LDY + ycol + e0) = o; } }
.LBB0_877:
	s_or_b64 exec, exec, s[0:1]
	v_or_b32_e32 v72, s9, v151
	s_lshl_b32 s9, s59, 1
	s_add_u32 s0, s26, s9
	s_addc_u32 s1, s27, 0
	v_or_b32_e32 v84, s58, v150
	v_mov_b64_e32 v[90:91], s[0:1]
	s_waitcnt lgkmcnt(0)
	v_mad_i64_i32 v[62:63], s[0:1], v84, s56, v[90:91]
	v_ashrrev_i32_e32 v73, 31, v72
	v_lshl_add_u64 v[74:75], v[62:63], 0, s[48:49]
	v_lshlrev_b64 v[82:83], 1, v[72:73]
	v_lshl_add_u64 v[76:77], v[74:75], 0, v[82:83]
	s_waitcnt vmcnt(0) lgkmcnt(0)
	s_barrier
	global_load_dwordx2 v[186:187], v[76:77], off
	v_lshl_add_u64 v[188:189], v[72:73], 2, s[62:63]
	global_load_dwordx4 v[190:193], v[188:189], off
	v_or_b32_e32 v194, s58, v146
	v_mad_i64_i32 v[196:197], s[0:1], v194, s56, v[90:91]
	v_lshl_add_u64 v[198:199], v[196:197], 0, s[48:49]
	v_lshl_add_u64 v[200:201], v[198:199], 0, v[82:83]
	global_load_dwordx2 v[202:203], v[200:201], off
	v_or_b32_e32 v204, 32, v84
	v_mad_i64_i32 v[206:207], s[0:1], v204, s56, v[90:91]
	v_lshl_add_u64 v[208:209], v[206:207], 0, s[48:49]
	v_lshl_add_u64 v[210:211], v[208:209], 0, v[82:83]
	v_or_b32_e32 v212, 48, v84
	global_load_dwordx2 v[214:215], v[210:211], off
	v_mad_i64_i32 v[216:217], s[0:1], v212, s56, v[90:91]
	v_lshl_add_u64 v[218:219], v[216:217], 0, s[48:49]
	v_lshl_add_u64 v[220:221], v[218:219], 0, v[82:83]
	global_load_dwordx2 v[222:223], v[220:221], off
	v_or_b32_e32 v224, 16, v72
	v_ashrrev_i32_e32 v225, 31, v224
	v_lshlrev_b64 v[226:227], 1, v[224:225]
	v_lshl_add_u64 v[228:229], v[74:75], 0, v[226:227]
	global_load_dwordx2 v[230:231], v[228:229], off
	global_load_dwordx4 v[232:235], v[188:189], off offset:64
	v_lshl_add_u64 v[236:237], v[198:199], 0, v[226:227]
	global_load_dwordx2 v[238:239], v[236:237], off
	v_lshl_add_u64 v[240:241], v[208:209], 0, v[226:227]
	global_load_dwordx2 v[242:243], v[240:241], off
	v_lshl_add_u64 v[244:245], v[218:219], 0, v[226:227]
	global_load_dwordx2 v[246:247], v[244:245], off
	v_or_b32_e32 v248, 32, v72
	v_ashrrev_i32_e32 v249, 31, v248
	v_lshlrev_b64 v[120:121], 1, v[248:249]
	v_lshl_add_u64 v[122:123], v[74:75], 0, v[120:121]
	global_load_dwordx2 v[124:125], v[122:123], off
	v_lshl_add_u64 v[126:127], v[198:199], 0, v[120:121]
	global_load_dwordx4 v[128:131], v[188:189], off offset:128
	global_load_dwordx2 v[132:133], v[126:127], off
	v_lshl_add_u64 v[134:135], v[208:209], 0, v[120:121]
	global_load_dwordx2 v[136:137], v[134:135], off
	v_lshl_add_u64 v[140:141], v[218:219], 0, v[120:121]
	global_load_dwordx2 v[142:143], v[140:141], off
	v_or_b32_e32 v144, 48, v72
	v_ashrrev_i32_e32 v145, 31, v144
	v_lshlrev_b64 v[148:149], 1, v[144:145]
	v_lshl_add_u64 v[152:153], v[74:75], 0, v[148:149]
	global_load_dwordx2 v[154:155], v[152:153], off
	v_lshl_add_u64 v[156:157], v[198:199], 0, v[148:149]
	global_load_dwordx4 v[172:175], v[188:189], off offset:192
	global_load_dwordx2 v[158:159], v[156:157], off
	v_lshl_add_u64 v[162:163], v[208:209], 0, v[148:149]
	global_load_dwordx2 v[166:167], v[162:163], off
	v_lshl_add_u64 v[176:177], v[218:219], 0, v[148:149]
	global_load_dwordx2 v[178:179], v[176:177], off
	v_lshl_add_u64 v[70:71], v[72:73], 2, s[62:63]
	v_lshl_add_u32 v16, v150, 2, 0
	v_add_u32_e32 v16, 0x24c00, v16
	ds_read2_b32 v[76:77], v16 offset1:16
	ds_read2_b32 v[80:81], v16 offset0:64 offset1:80
	ds_read2_b32 v[86:87], v16 offset0:128 offset1:144
	ds_read2_b32 v[108:109], v16 offset0:192 offset1:208
	v_add_u32_e32 v73, 0x400, v16
	s_waitcnt lgkmcnt(3)
	v_mov_b32_e32 v118, v77
	v_mov_b32_e32 v119, v76
	s_waitcnt lgkmcnt(2)
	v_mov_b32_e32 v76, v81
	v_mov_b32_e32 v77, v80
	s_waitcnt lgkmcnt(1)
	v_mov_b32_e32 v80, v87
	v_mov_b32_e32 v81, v86
	s_waitcnt lgkmcnt(0)
	v_mov_b32_e32 v86, v109
	v_mov_b32_e32 v87, v108
	v_pk_add_f32 v[108:109], v[118:119], 0 op_sel_hi:[1,0]
	ds_read2_b32 v[106:107], v16 offset0:32 offset1:48
	ds_read2_b32 v[102:103], v16 offset0:96 offset1:112
	ds_read2_b32 v[98:99], v16 offset0:160 offset1:176
	ds_read2_b32 v[94:95], v16 offset0:224 offset1:240
	ds_read2_b32 v[110:111], v73 offset1:16
	ds_read2_b32 v[112:113], v73 offset0:64 offset1:80
	ds_read2_b32 v[114:115], v73 offset0:128 offset1:144
	ds_read2_b32 v[116:117], v73 offset0:192 offset1:208
	ds_read2_b32 v[104:105], v73 offset0:32 offset1:48
	ds_read2_b32 v[100:101], v73 offset0:96 offset1:112
	ds_read2_b32 v[96:97], v73 offset0:160 offset1:176
	ds_read2_b32 v[92:93], v73 offset0:224 offset1:240
	v_pk_add_f32 v[76:77], v[108:109], v[76:77]
	s_waitcnt lgkmcnt(7)
	v_mov_b32_e32 v118, v111
	v_pk_add_f32 v[76:77], v[76:77], v[80:81]
	v_mov_b32_e32 v119, v110
	v_pk_add_f32 v[76:77], v[76:77], v[86:87]
	s_waitcnt lgkmcnt(6)
	v_mov_b32_e32 v110, v113
	v_mov_b32_e32 v111, v112
	v_pk_add_f32 v[76:77], v[76:77], v[118:119]
	s_waitcnt lgkmcnt(5)
	v_mov_b32_e32 v112, v115
	v_mov_b32_e32 v113, v114
	v_pk_add_f32 v[76:77], v[76:77], v[110:111]
	s_mov_b32 s0, 0x358637bd
	s_waitcnt lgkmcnt(4)
	v_mov_b32_e32 v114, v117
	v_mov_b32_e32 v115, v116
	v_pk_add_f32 v[76:77], v[76:77], v[112:113]
	v_mov_b64_e32 v[88:89], s[0:1]
	v_mov_b32_e32 v85, s8
	v_pk_add_f32 v[76:77], v[76:77], v[114:115]
	s_mov_b32 s8, 0x3b000000
	v_pk_fma_f32 v[76:77], v[76:77], s[8:9], v[88:89] op_sel_hi:[1,0,0]
	s_add_u32 s0, s61, s9
	v_mul_f32_e32 v16, 0x4b800000, v77
	v_cmp_gt_f32_e32 vcc, s33, v77
	v_readlane_b32 s1, v253, 31
	s_addc_u32 s1, s1, 0
	v_cndmask_b32_e32 v16, v77, v16, vcc
	v_rsq_f32_e32 v16, v16
	v_lshl_add_u64 v[86:87], s[0:1], 0, v[82:83]
	s_add_i32 s37, s37, s70
	s_add_i32 s36, s36, s70
	v_mul_f32_e32 v73, 0x45800000, v16
	v_cndmask_b32_e32 v16, v16, v73, vcc
	v_pk_mul_f32 v[66:67], v[66:67], v[16:17] op_sel_hi:[1,0]
	v_pk_mul_f32 v[68:69], v[68:69], v[16:17] op_sel_hi:[1,0]
	v_cmp_gt_f32_e32 vcc, s33, v76
	v_pk_mul_f32 v[46:47], v[46:47], v[16:17] op_sel_hi:[1,0]
	v_pk_mul_f32 v[48:49], v[48:49], v[16:17] op_sel_hi:[1,0]
	v_pk_mul_f32 v[30:31], v[30:31], v[16:17] op_sel_hi:[1,0]
	v_pk_mul_f32 v[32:33], v[32:33], v[16:17] op_sel_hi:[1,0]
	v_pk_mul_f32 v[12:13], v[12:13], v[16:17] op_sel_hi:[1,0]
	v_pk_mul_f32 v[14:15], v[14:15], v[16:17] op_sel_hi:[1,0]
	s_cmpk_lt_i32 s37, 0x400
	s_waitcnt vmcnt(0)
; __device__ __forceinline__ unsigned pk2(float lo, float hi) { return pg8::cvt_pk_bf16(lo, hi); }
; __device__ __forceinline__ float siluf(float x) { return x * __builtin_amdgcn_rcpf(1.0f + __expf(-x)); }
; template <int TY> __device__ __forceinline__ void mc_item(const Params& p, ldsp lds, int item) {
;     ...
;     for (int ei = 0; ei < ET; ++ei) { const int e0 = 16 * (wave * ET + ei) + 4 * q4; const f32x4 w4 = *(const f32x4*)(nwp + e0);
; #pragma unroll
;         for (int tk = 0; tk < 4; ++tk) { const size_t row = (size_t)row0 + 16 * tk + l15;
;             const u32x2 gw = *(const u32x2*)(Pb + row * PP + goff + e0);
;             const float g0 = bf2f(gw.x & 0xffffu), g1 = bf2f(gw.x >> 16), g2 = bf2f(gw.y & 0xffffu), g3 = bf2f(gw.y >> 16);
;             const f32x4 v = acc[ei][tk] * rstd[tk] * w4;
;             float y0 = v[0] * siluf(g0), y1 = v[1] * siluf(g1), y2 = v[2] * siluf(g2), y3 = v[3] * siluf(g3);
;     ...
;             if (!(fabsf(y0) < 1e30f)) y0 = 0.f; if (!(fabsf(y1) < 1e30f)) y1 = 0.f; if (!(fabsf(y2) < 1e30f)) y2 = 0.f; if (!(fabsf(y3) < 1e30f)) y3 = 0.f;
;     ...
;             u32x2 o; o.x = pk2(y0, y1); o.y = pk2(y2, y3);
;             *(u32x2*)(Y + row * LDY + ycol + e0) = o; } }
	v_lshlrev_b32_e32 v73, 16, v186
	v_mul_f32_e32 v80, 0xbfb8aa3b, v73
	v_exp_f32_e32 v80, v80
	v_and_b32_e32 v77, 0xffff0000, v186
	v_lshlrev_b32_e32 v78, 16, v187
	v_and_b32_e32 v79, 0xffff0000, v187
	v_mul_f32_e32 v81, 0xbfb8aa3b, v77
	v_mul_f32_e32 v108, 0xbfb8aa3b, v78
	v_mul_f32_e32 v109, 0xbfb8aa3b, v79
	v_exp_f32_e32 v81, v81
	v_add_f32_e32 v80, 1.0, v80
	v_exp_f32_e32 v108, v108
	v_exp_f32_e32 v109, v109
	v_rcp_f32_e32 v80, v80
	v_add_f32_e32 v81, 1.0, v81
	v_pk_mul_f32 v[66:67], v[66:67], v[190:191]
	v_add_f32_e32 v108, 1.0, v108
	v_rcp_f32_e32 v81, v81
	v_add_f32_e32 v109, 1.0, v109
	v_mul_f32_e32 v73, v80, v73
	v_rcp_f32_e32 v108, v108
	v_mul_f32_e32 v66, v66, v73
	v_rcp_f32_e32 v73, v109
	v_mul_f32_e32 v77, v81, v77
	v_pk_mul_f32 v[68:69], v[68:69], v[192:193]
	v_mul_f32_e32 v67, v67, v77
	v_mul_f32_e32 v77, v108, v78
	v_mul_f32_e32 v73, v73, v79
	v_mul_f32_e32 v68, v68, v77
	v_mul_f32_e32 v69, v69, v73
	v_cvt_pk_bf16_f32 v66, v66, v67
	v_cvt_pk_bf16_f32 v67, v68, v69
	v_lshlrev_b64 v[68:69], 12, v[84:85]
	v_lshl_add_u64 v[78:79], v[86:87], 0, v[68:69]
	global_store_dwordx2 v[78:79], v[66:67], off
	v_or_b32_e32 v66, s58, v146
	v_mad_i64_i32 v[68:69], s[0:1], v66, s56, v[90:91]
	v_lshl_add_u64 v[80:81], v[68:69], 0, s[48:49]
	v_lshl_add_u64 v[68:69], v[80:81], 0, v[82:83]
	v_mul_f32_e32 v73, 0x4b800000, v76
	v_cndmask_b32_e32 v73, v76, v73, vcc
	v_rsq_f32_e32 v73, v73
	v_mov_b32_e32 v67, v85
	v_or_b32_e32 v108, 32, v84
	v_lshlrev_b64 v[66:67], 12, v[66:67]
	v_mul_f32_e32 v76, 0x45800000, v73
	v_cndmask_b32_e32 v76, v73, v76, vcc
	v_pk_mul_f32 v[58:59], v[58:59], v[76:77] op_sel_hi:[1,0]
	v_pk_mul_f32 v[60:61], v[60:61], v[76:77] op_sel_hi:[1,0]
	v_mad_i64_i32 v[68:69], s[0:1], v108, s56, v[90:91]
	v_pk_mul_f32 v[58:59], v[58:59], v[190:191]
	v_lshl_add_u64 v[68:69], v[68:69], 0, s[48:49]
	v_lshl_add_u64 v[66:67], v[86:87], 0, v[66:67]
	v_pk_mul_f32 v[60:61], v[60:61], v[192:193]
	v_lshl_add_u64 v[112:113], v[68:69], 0, v[82:83]
	v_or_b32_e32 v84, 48, v84
	v_lshlrev_b32_e32 v73, 16, v202
	v_and_b32_e32 v77, 0xffff0000, v202
	v_lshlrev_b32_e32 v109, 16, v203
	v_and_b32_e32 v110, 0xffff0000, v203
	v_mul_f32_e32 v111, 0xbfb8aa3b, v73
	v_mul_f32_e32 v114, 0xbfb8aa3b, v77
	v_mul_f32_e32 v115, 0xbfb8aa3b, v109
	v_mul_f32_e32 v116, 0xbfb8aa3b, v110
	v_exp_f32_e32 v111, v111
	v_exp_f32_e32 v114, v114
	v_exp_f32_e32 v115, v115
	v_exp_f32_e32 v116, v116
	v_add_f32_e32 v111, 1.0, v111
	v_add_f32_e32 v114, 1.0, v114
	v_add_f32_e32 v115, 1.0, v115
	v_add_f32_e32 v116, 1.0, v116
	v_rcp_f32_e32 v111, v111
	v_rcp_f32_e32 v114, v114
	v_rcp_f32_e32 v115, v115
	v_rcp_f32_e32 v116, v116
	v_mul_f32_e32 v73, v111, v73
	v_mul_f32_e32 v77, v114, v77
	v_mul_f32_e32 v109, v115, v109
	v_mul_f32_e32 v110, v116, v110
	v_mul_f32_e32 v58, v58, v73
	v_mul_f32_e32 v59, v59, v77
	v_mul_f32_e32 v60, v60, v109
	v_mul_f32_e32 v61, v61, v110
	v_cvt_pk_bf16_f32 v58, v58, v59
	v_cvt_pk_bf16_f32 v59, v60, v61
	global_store_dwordx2 v[66:67], v[58:59], off
	v_mad_i64_i32 v[60:61], s[0:1], v84, s56, v[90:91]
	v_mov_b32_e32 v90, v107
	v_mov_b32_e32 v91, v106
	v_mov_b32_e32 v106, v103
	v_mov_b32_e32 v107, v102
	v_pk_add_f32 v[90:91], v[90:91], 0 op_sel_hi:[1,0]
	v_mov_b32_e32 v102, v99
	v_mov_b32_e32 v103, v98
	v_pk_add_f32 v[90:91], v[90:91], v[106:107]
	v_mov_b32_e32 v98, v95
	v_mov_b32_e32 v99, v94
	v_pk_add_f32 v[90:91], v[90:91], v[102:103]
	s_waitcnt lgkmcnt(3)
	v_mov_b32_e32 v94, v105
	v_mov_b32_e32 v95, v104
	v_pk_add_f32 v[90:91], v[90:91], v[98:99]
	s_waitcnt lgkmcnt(2)
	v_mov_b32_e32 v104, v101
	v_mov_b32_e32 v105, v100
	v_pk_add_f32 v[90:91], v[90:91], v[94:95]
	s_waitcnt lgkmcnt(1)
	v_mov_b32_e32 v100, v97
	v_mov_b32_e32 v101, v96
	v_pk_add_f32 v[90:91], v[90:91], v[104:105]
	s_waitcnt lgkmcnt(0)
	v_mov_b32_e32 v96, v93
	v_mov_b32_e32 v97, v92
	v_pk_add_f32 v[90:91], v[90:91], v[100:101]
	v_lshl_add_u64 v[60:61], v[60:61], 0, s[48:49]
	v_pk_add_f32 v[90:91], v[90:91], v[96:97]
	v_mov_b32_e32 v109, v85
	v_pk_fma_f32 v[88:89], v[90:91], s[8:9], v[88:89] op_sel_hi:[1,0,0]
	v_lshl_add_u64 v[90:91], v[60:61], 0, v[82:83]
	v_mul_f32_e32 v73, 0x4b800000, v89
	v_cmp_gt_f32_e32 vcc, s33, v89
	v_lshlrev_b64 v[58:59], 12, v[108:109]
	v_lshl_add_u64 v[58:59], v[86:87], 0, v[58:59]
	v_cndmask_b32_e32 v73, v89, v73, vcc
	v_rsq_f32_e32 v73, v73
	v_and_b32_e32 v89, 0xffff0000, v215
	v_mul_f32_e32 v77, 0x45800000, v73
	v_cndmask_b32_e32 v82, v73, v77, vcc
	v_lshlrev_b32_e32 v73, 16, v214
	v_and_b32_e32 v77, 0xffff0000, v214
	v_pk_mul_f32 v[54:55], v[54:55], v[82:83] op_sel_hi:[1,0]
	v_pk_mul_f32 v[56:57], v[56:57], v[82:83] op_sel_hi:[1,0]
	v_lshlrev_b32_e32 v83, 16, v215
	v_mul_f32_e32 v92, 0xbfb8aa3b, v73
	v_mul_f32_e32 v93, 0xbfb8aa3b, v77
	v_mul_f32_e32 v94, 0xbfb8aa3b, v83
	v_mul_f32_e32 v95, 0xbfb8aa3b, v89
	v_exp_f32_e32 v92, v92
	v_exp_f32_e32 v93, v93
	v_exp_f32_e32 v94, v94
	v_exp_f32_e32 v95, v95
	v_add_f32_e32 v92, 1.0, v92
	v_add_f32_e32 v93, 1.0, v93
	v_add_f32_e32 v94, 1.0, v94
	v_add_f32_e32 v95, 1.0, v95
	v_rcp_f32_e32 v92, v92
	v_rcp_f32_e32 v93, v93
	v_rcp_f32_e32 v94, v94
	v_rcp_f32_e32 v95, v95
	v_pk_mul_f32 v[54:55], v[190:191], v[54:55]
	v_mul_f32_e32 v73, v92, v73
	v_mul_f32_e32 v77, v93, v77
	v_pk_mul_f32 v[56:57], v[192:193], v[56:57]
	v_mul_f32_e32 v83, v94, v83
	v_mul_f32_e32 v89, v95, v89
	v_mul_f32_e32 v54, v54, v73
	v_mul_f32_e32 v55, v55, v77
	v_mul_f32_e32 v56, v56, v83
	v_mul_f32_e32 v57, v57, v89
	v_cvt_pk_bf16_f32 v54, v54, v55
	v_cvt_pk_bf16_f32 v55, v56, v57
	global_store_dwordx2 v[58:59], v[54:55], off
	v_mul_f32_e32 v57, 0x4b800000, v88
	v_cmp_gt_f32_e32 vcc, s33, v88
	v_or_b32_e32 v56, 16, v72
	s_nop 0
	v_cndmask_b32_e32 v57, v88, v57, vcc
; __device__ __forceinline__ unsigned pk2(float lo, float hi) { return pg8::cvt_pk_bf16(lo, hi); }
; __device__ __forceinline__ float siluf(float x) { return x * __builtin_amdgcn_rcpf(1.0f + __expf(-x)); }
; template <int TY> __device__ __forceinline__ void mc_item(const Params& p, ldsp lds, int item) {
;     ...
;     for (int ei = 0; ei < ET; ++ei) { const int e0 = 16 * (wave * ET + ei) + 4 * q4; const f32x4 w4 = *(const f32x4*)(nwp + e0);
; #pragma unroll
;         for (int tk = 0; tk < 4; ++tk) { const size_t row = (size_t)row0 + 16 * tk + l15;
;             const u32x2 gw = *(const u32x2*)(Pb + row * PP + goff + e0);
;             const float g0 = bf2f(gw.x & 0xffffu), g1 = bf2f(gw.x >> 16), g2 = bf2f(gw.y & 0xffffu), g3 = bf2f(gw.y >> 16);
;             const f32x4 v = acc[ei][tk] * rstd[tk] * w4;
;             float y0 = v[0] * siluf(g0), y1 = v[1] * siluf(g1), y2 = v[2] * siluf(g2), y3 = v[3] * siluf(g3);
;     ...
;             if (!(fabsf(y0) < 1e30f)) y0 = 0.f; if (!(fabsf(y1) < 1e30f)) y1 = 0.f; if (!(fabsf(y2) < 1e30f)) y2 = 0.f; if (!(fabsf(y3) < 1e30f)) y3 = 0.f;
;     ...
;             u32x2 o; o.x = pk2(y0, y1); o.y = pk2(y2, y3);
;             *(u32x2*)(Y + row * LDY + ycol + e0) = o; } }
	v_rsq_f32_e32 v73, v57
	v_ashrrev_i32_e32 v57, 31, v56
	v_lshlrev_b64 v[88:89], 1, v[56:57]
	v_lshl_add_u64 v[90:91], v[74:75], 0, v[88:89]
	v_mul_f32_e32 v56, 0x45800000, v73
	v_cndmask_b32_e32 v56, v73, v56, vcc
	v_pk_mul_f32 v[50:51], v[50:51], v[56:57] op_sel_hi:[1,0]
	v_pk_mul_f32 v[52:53], v[52:53], v[56:57] op_sel_hi:[1,0]
	v_pk_mul_f32 v[50:51], v[190:191], v[50:51]
	v_pk_mul_f32 v[52:53], v[192:193], v[52:53]
	v_lshlrev_b32_e32 v57, 16, v222
	v_and_b32_e32 v54, 0xffff0000, v222
	v_lshlrev_b32_e32 v62, 16, v223
	v_and_b32_e32 v55, 0xffff0000, v223
	v_mul_f32_e32 v63, 0xbfb8aa3b, v57
	v_mul_f32_e32 v64, 0xbfb8aa3b, v54
	v_mul_f32_e32 v65, 0xbfb8aa3b, v62
	v_mul_f32_e32 v73, 0xbfb8aa3b, v55
	v_exp_f32_e32 v63, v63
	v_exp_f32_e32 v64, v64
	v_exp_f32_e32 v65, v65
	v_exp_f32_e32 v73, v73
	v_add_f32_e32 v63, 1.0, v63
	v_add_f32_e32 v64, 1.0, v64
	v_add_f32_e32 v65, 1.0, v65
	v_add_f32_e32 v73, 1.0, v73
	v_rcp_f32_e32 v63, v63
	v_rcp_f32_e32 v64, v64
	v_rcp_f32_e32 v65, v65
	v_rcp_f32_e32 v73, v73
	v_mul_f32_e32 v57, v63, v57
	v_mul_f32_e32 v54, v64, v54
	v_mul_f32_e32 v62, v65, v62
	v_mul_f32_e32 v55, v73, v55
	v_mul_f32_e32 v50, v50, v57
	v_mul_f32_e32 v51, v51, v54
	v_mul_f32_e32 v52, v52, v62
	v_mul_f32_e32 v53, v53, v55
	v_cvt_pk_bf16_f32 v50, v50, v51
	v_cvt_pk_bf16_f32 v51, v52, v53
	v_lshlrev_b64 v[52:53], 12, v[84:85]
	v_lshl_add_u64 v[54:55], v[86:87], 0, v[52:53]
	global_store_dwordx2 v[54:55], v[50:51], off
	v_lshl_add_u64 v[64:65], v[80:81], 0, v[88:89]
	v_lshlrev_b32_e32 v57, 16, v230
	v_and_b32_e32 v62, 0xffff0000, v230
	v_lshlrev_b32_e32 v73, 16, v231
	v_and_b32_e32 v63, 0xffff0000, v231
	v_mul_f32_e32 v77, 0xbfb8aa3b, v57
	v_mul_f32_e32 v83, 0xbfb8aa3b, v62
	v_mul_f32_e32 v84, 0xbfb8aa3b, v73
	v_mul_f32_e32 v85, 0xbfb8aa3b, v63
	v_exp_f32_e32 v77, v77
	v_exp_f32_e32 v83, v83
	v_exp_f32_e32 v84, v84
	v_exp_f32_e32 v85, v85
	v_add_f32_e32 v77, 1.0, v77
	v_add_f32_e32 v83, 1.0, v83
	v_add_f32_e32 v84, 1.0, v84
	v_add_f32_e32 v85, 1.0, v85
	v_rcp_f32_e32 v77, v77
	v_rcp_f32_e32 v83, v83
	v_rcp_f32_e32 v84, v84
	v_rcp_f32_e32 v85, v85
	v_pk_mul_f32 v[46:47], v[46:47], v[232:233]
	v_mul_f32_e32 v57, v77, v57
	v_mul_f32_e32 v62, v83, v62
	v_pk_mul_f32 v[48:49], v[48:49], v[234:235]
	v_mul_f32_e32 v73, v84, v73
	v_mul_f32_e32 v63, v85, v63
	v_mul_f32_e32 v46, v46, v57
	v_mul_f32_e32 v47, v47, v62
	v_mul_f32_e32 v48, v48, v73
	v_mul_f32_e32 v49, v49, v63
	v_cvt_pk_bf16_f32 v46, v46, v47
	v_cvt_pk_bf16_f32 v47, v48, v49
	global_store_dwordx2 v[78:79], v[46:47], off offset:32
	v_pk_mul_f32 v[42:43], v[42:43], v[76:77] op_sel_hi:[1,0]
	v_pk_mul_f32 v[44:45], v[44:45], v[76:77] op_sel_hi:[1,0]
	v_pk_mul_f32 v[42:43], v[42:43], v[232:233]
	v_pk_mul_f32 v[44:45], v[44:45], v[234:235]
	v_lshl_add_u64 v[48:49], v[68:69], 0, v[88:89]
	v_pk_mul_f32 v[38:39], v[38:39], v[82:83] op_sel_hi:[1,0]
	v_pk_mul_f32 v[40:41], v[40:41], v[82:83] op_sel_hi:[1,0]
	v_pk_mul_f32 v[38:39], v[38:39], v[232:233]
	v_pk_mul_f32 v[40:41], v[40:41], v[234:235]
	v_pk_mul_f32 v[26:27], v[26:27], v[76:77] op_sel_hi:[1,0]
	v_pk_mul_f32 v[28:29], v[28:29], v[76:77] op_sel_hi:[1,0]
	v_pk_mul_f32 v[22:23], v[22:23], v[82:83] op_sel_hi:[1,0]
	v_pk_mul_f32 v[24:25], v[24:25], v[82:83] op_sel_hi:[1,0]
	v_pk_mul_f32 v[8:9], v[8:9], v[76:77] op_sel_hi:[1,0]
	v_pk_mul_f32 v[10:11], v[10:11], v[76:77] op_sel_hi:[1,0]
	v_pk_mul_f32 v[4:5], v[4:5], v[82:83] op_sel_hi:[1,0]
	v_pk_mul_f32 v[6:7], v[6:7], v[82:83] op_sel_hi:[1,0]
	v_lshlrev_b32_e32 v57, 16, v238
	v_and_b32_e32 v46, 0xffff0000, v238
	v_lshlrev_b32_e32 v62, 16, v239
	v_and_b32_e32 v47, 0xffff0000, v239
	v_mul_f32_e32 v63, 0xbfb8aa3b, v57
	v_mul_f32_e32 v64, 0xbfb8aa3b, v46
	v_mul_f32_e32 v65, 0xbfb8aa3b, v62
	v_mul_f32_e32 v73, 0xbfb8aa3b, v47
	v_exp_f32_e32 v63, v63
	v_exp_f32_e32 v64, v64
	v_exp_f32_e32 v65, v65
	v_exp_f32_e32 v73, v73
	v_add_f32_e32 v63, 1.0, v63
	v_add_f32_e32 v64, 1.0, v64
	v_add_f32_e32 v65, 1.0, v65
	v_add_f32_e32 v73, 1.0, v73
	v_rcp_f32_e32 v63, v63
	v_rcp_f32_e32 v64, v64
	v_rcp_f32_e32 v65, v65
	v_rcp_f32_e32 v73, v73
	v_mul_f32_e32 v57, v63, v57
	v_mul_f32_e32 v46, v64, v46
	v_mul_f32_e32 v62, v65, v62
	v_mul_f32_e32 v47, v73, v47
	v_mul_f32_e32 v42, v42, v57
	v_mul_f32_e32 v43, v43, v46
	v_mul_f32_e32 v44, v44, v62
	v_mul_f32_e32 v45, v45, v47
	v_cvt_pk_bf16_f32 v42, v42, v43
	v_cvt_pk_bf16_f32 v43, v44, v45
	global_store_dwordx2 v[66:67], v[42:43], off offset:32
	v_lshl_add_u64 v[44:45], v[60:61], 0, v[88:89]
	v_lshlrev_b32_e32 v46, 16, v242
	v_and_b32_e32 v42, 0xffff0000, v242
	v_lshlrev_b32_e32 v47, 16, v243
	v_and_b32_e32 v43, 0xffff0000, v243
	v_mul_f32_e32 v48, 0xbfb8aa3b, v46
	v_mul_f32_e32 v49, 0xbfb8aa3b, v42
	v_mul_f32_e32 v57, 0xbfb8aa3b, v47
	v_mul_f32_e32 v62, 0xbfb8aa3b, v43
	v_exp_f32_e32 v48, v48
	v_exp_f32_e32 v49, v49
	v_exp_f32_e32 v57, v57
	v_exp_f32_e32 v62, v62
	v_add_f32_e32 v48, 1.0, v48
	v_add_f32_e32 v49, 1.0, v49
	v_add_f32_e32 v57, 1.0, v57
	v_add_f32_e32 v62, 1.0, v62
	v_rcp_f32_e32 v48, v48
	v_rcp_f32_e32 v49, v49
	v_rcp_f32_e32 v57, v57
	v_rcp_f32_e32 v62, v62
	v_mul_f32_e32 v46, v48, v46
	v_mul_f32_e32 v42, v49, v42
	v_mul_f32_e32 v47, v57, v47
	v_mul_f32_e32 v43, v62, v43
	v_mul_f32_e32 v38, v38, v46
	v_mul_f32_e32 v39, v39, v42
	v_mul_f32_e32 v40, v40, v47
	v_mul_f32_e32 v41, v41, v43
	v_cvt_pk_bf16_f32 v38, v38, v39
	v_cvt_pk_bf16_f32 v39, v40, v41
	global_store_dwordx2 v[58:59], v[38:39], off offset:32
	v_or_b32_e32 v38, 32, v72
	v_ashrrev_i32_e32 v39, 31, v38
	v_pk_mul_f32 v[34:35], v[34:35], v[56:57] op_sel_hi:[1,0]
	v_lshlrev_b64 v[38:39], 1, v[38:39]
	v_pk_mul_f32 v[36:37], v[36:37], v[56:57] op_sel_hi:[1,0]
	v_pk_mul_f32 v[34:35], v[34:35], v[232:233]
; __device__ __forceinline__ unsigned pk2(float lo, float hi) { return pg8::cvt_pk_bf16(lo, hi); }
; __device__ __forceinline__ float siluf(float x) { return x * __builtin_amdgcn_rcpf(1.0f + __expf(-x)); }
; template <int TY> __device__ __forceinline__ void mc_item(const Params& p, ldsp lds, int item) {
;     ...
;     for (int ei = 0; ei < ET; ++ei) { const int e0 = 16 * (wave * ET + ei) + 4 * q4; const f32x4 w4 = *(const f32x4*)(nwp + e0);
; #pragma unroll
;         for (int tk = 0; tk < 4; ++tk) { const size_t row = (size_t)row0 + 16 * tk + l15;
;             const u32x2 gw = *(const u32x2*)(Pb + row * PP + goff + e0);
;             const float g0 = bf2f(gw.x & 0xffffu), g1 = bf2f(gw.x >> 16), g2 = bf2f(gw.y & 0xffffu), g3 = bf2f(gw.y >> 16);
;             const f32x4 v = acc[ei][tk] * rstd[tk] * w4;
;             float y0 = v[0] * siluf(g0), y1 = v[1] * siluf(g1), y2 = v[2] * siluf(g2), y3 = v[3] * siluf(g3);
;     ...
;             if (!(fabsf(y0) < 1e30f)) y0 = 0.f; if (!(fabsf(y1) < 1e30f)) y1 = 0.f; if (!(fabsf(y2) < 1e30f)) y2 = 0.f; if (!(fabsf(y3) < 1e30f)) y3 = 0.f;
;     ...
;             u32x2 o; o.x = pk2(y0, y1); o.y = pk2(y2, y3);
;             *(u32x2*)(Y + row * LDY + ycol + e0) = o; } }
	v_lshl_add_u64 v[42:43], v[74:75], 0, v[38:39]
	v_pk_mul_f32 v[36:37], v[36:37], v[234:235]
	v_pk_mul_f32 v[18:19], v[18:19], v[56:57] op_sel_hi:[1,0]
	v_pk_mul_f32 v[20:21], v[20:21], v[56:57] op_sel_hi:[1,0]
	v_pk_mul_f32 v[0:1], v[0:1], v[56:57] op_sel_hi:[1,0]
	v_pk_mul_f32 v[2:3], v[2:3], v[56:57] op_sel_hi:[1,0]
	v_lshlrev_b32_e32 v44, 16, v246
	v_and_b32_e32 v40, 0xffff0000, v246
	v_lshlrev_b32_e32 v45, 16, v247
	v_and_b32_e32 v41, 0xffff0000, v247
	v_mul_f32_e32 v46, 0xbfb8aa3b, v44
	v_mul_f32_e32 v47, 0xbfb8aa3b, v40
	v_mul_f32_e32 v48, 0xbfb8aa3b, v45
	v_mul_f32_e32 v49, 0xbfb8aa3b, v41
	v_exp_f32_e32 v46, v46
	v_exp_f32_e32 v47, v47
	v_exp_f32_e32 v48, v48
	v_exp_f32_e32 v49, v49
	v_add_f32_e32 v46, 1.0, v46
	v_add_f32_e32 v47, 1.0, v47
	v_add_f32_e32 v48, 1.0, v48
	v_add_f32_e32 v49, 1.0, v49
	v_rcp_f32_e32 v46, v46
	v_rcp_f32_e32 v47, v47
	v_rcp_f32_e32 v48, v48
	v_rcp_f32_e32 v49, v49
	v_mul_f32_e32 v44, v46, v44
	v_mul_f32_e32 v40, v47, v40
	v_mul_f32_e32 v45, v48, v45
	v_mul_f32_e32 v41, v49, v41
	v_mul_f32_e32 v34, v34, v44
	v_mul_f32_e32 v35, v35, v40
	v_mul_f32_e32 v36, v36, v45
	v_mul_f32_e32 v37, v37, v41
	v_cvt_pk_bf16_f32 v34, v34, v35
	v_cvt_pk_bf16_f32 v35, v36, v37
	v_lshl_add_u64 v[42:43], v[80:81], 0, v[38:39]
	global_store_dwordx2 v[54:55], v[34:35], off offset:32
	v_lshlrev_b32_e32 v44, 16, v124
	v_and_b32_e32 v40, 0xffff0000, v124
	v_lshlrev_b32_e32 v45, 16, v125
	v_and_b32_e32 v41, 0xffff0000, v125
	v_mul_f32_e32 v46, 0xbfb8aa3b, v44
	v_mul_f32_e32 v47, 0xbfb8aa3b, v40
	v_mul_f32_e32 v48, 0xbfb8aa3b, v45
	v_mul_f32_e32 v49, 0xbfb8aa3b, v41
	v_exp_f32_e32 v46, v46
	v_exp_f32_e32 v47, v47
	v_exp_f32_e32 v48, v48
	v_exp_f32_e32 v49, v49
	v_add_f32_e32 v46, 1.0, v46
	v_add_f32_e32 v47, 1.0, v47
	v_add_f32_e32 v48, 1.0, v48
	v_add_f32_e32 v49, 1.0, v49
	v_rcp_f32_e32 v46, v46
	v_rcp_f32_e32 v47, v47
	v_rcp_f32_e32 v48, v48
	v_rcp_f32_e32 v49, v49
	v_pk_mul_f32 v[30:31], v[30:31], v[128:129]
	v_mul_f32_e32 v44, v46, v44
	v_mul_f32_e32 v40, v47, v40
	v_pk_mul_f32 v[32:33], v[32:33], v[130:131]
	v_mul_f32_e32 v45, v48, v45
	v_mul_f32_e32 v41, v49, v41
	v_mul_f32_e32 v30, v30, v44
	v_mul_f32_e32 v31, v31, v40
	v_mul_f32_e32 v32, v32, v45
	v_mul_f32_e32 v33, v33, v41
	v_cvt_pk_bf16_f32 v30, v30, v31
	v_cvt_pk_bf16_f32 v31, v32, v33
	global_store_dwordx2 v[78:79], v[30:31], off offset:64
	v_pk_mul_f32 v[26:27], v[26:27], v[128:129]
	v_pk_mul_f32 v[28:29], v[28:29], v[130:131]
	v_lshl_add_u64 v[32:33], v[68:69], 0, v[38:39]
	v_pk_mul_f32 v[22:23], v[22:23], v[128:129]
	v_pk_mul_f32 v[24:25], v[24:25], v[130:131]
	v_pk_mul_f32 v[18:19], v[18:19], v[128:129]
	v_pk_mul_f32 v[20:21], v[20:21], v[130:131]
	v_lshlrev_b32_e32 v40, 16, v132
	v_and_b32_e32 v30, 0xffff0000, v132
	v_lshlrev_b32_e32 v41, 16, v133
	v_and_b32_e32 v31, 0xffff0000, v133
	v_mul_f32_e32 v42, 0xbfb8aa3b, v40
	v_mul_f32_e32 v43, 0xbfb8aa3b, v30
	v_mul_f32_e32 v44, 0xbfb8aa3b, v41
	v_mul_f32_e32 v45, 0xbfb8aa3b, v31
	v_exp_f32_e32 v42, v42
	v_exp_f32_e32 v43, v43
	v_exp_f32_e32 v44, v44
	v_exp_f32_e32 v45, v45
	v_add_f32_e32 v42, 1.0, v42
	v_add_f32_e32 v43, 1.0, v43
	v_add_f32_e32 v44, 1.0, v44
	v_add_f32_e32 v45, 1.0, v45
	v_rcp_f32_e32 v42, v42
	v_rcp_f32_e32 v43, v43
	v_rcp_f32_e32 v44, v44
	v_rcp_f32_e32 v45, v45
	v_mul_f32_e32 v40, v42, v40
	v_mul_f32_e32 v30, v43, v30
	v_mul_f32_e32 v41, v44, v41
	v_mul_f32_e32 v31, v45, v31
	v_mul_f32_e32 v26, v26, v40
	v_mul_f32_e32 v27, v27, v30
	v_mul_f32_e32 v28, v28, v41
	v_mul_f32_e32 v29, v29, v31
	v_cvt_pk_bf16_f32 v26, v26, v27
	v_cvt_pk_bf16_f32 v27, v28, v29
	global_store_dwordx2 v[66:67], v[26:27], off offset:64
	v_lshl_add_u64 v[28:29], v[60:61], 0, v[38:39]
	v_lshlrev_b32_e32 v30, 16, v136
	v_and_b32_e32 v26, 0xffff0000, v136
	v_lshlrev_b32_e32 v31, 16, v137
	v_and_b32_e32 v27, 0xffff0000, v137
	v_mul_f32_e32 v32, 0xbfb8aa3b, v30
	v_mul_f32_e32 v33, 0xbfb8aa3b, v26
	v_mul_f32_e32 v38, 0xbfb8aa3b, v31
	v_mul_f32_e32 v39, 0xbfb8aa3b, v27
	v_exp_f32_e32 v32, v32
	v_exp_f32_e32 v33, v33
	v_exp_f32_e32 v38, v38
	v_exp_f32_e32 v39, v39
	v_add_f32_e32 v32, 1.0, v32
	v_add_f32_e32 v33, 1.0, v33
	v_add_f32_e32 v38, 1.0, v38
	v_add_f32_e32 v39, 1.0, v39
	v_rcp_f32_e32 v32, v32
	v_rcp_f32_e32 v33, v33
	v_rcp_f32_e32 v38, v38
	v_rcp_f32_e32 v39, v39
	v_mul_f32_e32 v30, v32, v30
	v_mul_f32_e32 v26, v33, v26
	v_mul_f32_e32 v31, v38, v31
	v_mul_f32_e32 v27, v39, v27
	v_mul_f32_e32 v22, v22, v30
	v_mul_f32_e32 v23, v23, v26
	v_mul_f32_e32 v24, v24, v31
	v_mul_f32_e32 v25, v25, v27
	v_cvt_pk_bf16_f32 v22, v22, v23
	v_cvt_pk_bf16_f32 v23, v24, v25
	global_store_dwordx2 v[58:59], v[22:23], off offset:64
	v_or_b32_e32 v22, 48, v72
	v_ashrrev_i32_e32 v23, 31, v22
	v_lshlrev_b64 v[22:23], 1, v[22:23]
	v_lshl_add_u64 v[26:27], v[74:75], 0, v[22:23]
	v_lshlrev_b32_e32 v28, 16, v142
	v_and_b32_e32 v24, 0xffff0000, v142
	v_lshlrev_b32_e32 v29, 16, v143
	v_and_b32_e32 v25, 0xffff0000, v143
	v_mul_f32_e32 v30, 0xbfb8aa3b, v28
	v_mul_f32_e32 v31, 0xbfb8aa3b, v24
	v_mul_f32_e32 v32, 0xbfb8aa3b, v29
	v_mul_f32_e32 v33, 0xbfb8aa3b, v25
	v_exp_f32_e32 v30, v30
	v_exp_f32_e32 v31, v31
	v_exp_f32_e32 v32, v32
	v_exp_f32_e32 v33, v33
	v_add_f32_e32 v30, 1.0, v30
; __device__ __forceinline__ unsigned pk2(float lo, float hi) { return pg8::cvt_pk_bf16(lo, hi); }
; __device__ __forceinline__ float siluf(float x) { return x * __builtin_amdgcn_rcpf(1.0f + __expf(-x)); }
; #define BSYNC() do { asm volatile("s_waitcnt vmcnt(0) lgkmcnt(0)" ::: "memory"); __syncthreads(); } while (0)
; template <int TY> __device__ __forceinline__ void mc_item(const Params& p, ldsp lds, int item) {
;     ...
;     for (int ei = 0; ei < ET; ++ei) { const int e0 = 16 * (wave * ET + ei) + 4 * q4; const f32x4 w4 = *(const f32x4*)(nwp + e0);
; #pragma unroll
;         for (int tk = 0; tk < 4; ++tk) { const size_t row = (size_t)row0 + 16 * tk + l15;
;             const u32x2 gw = *(const u32x2*)(Pb + row * PP + goff + e0);
;             const float g0 = bf2f(gw.x & 0xffffu), g1 = bf2f(gw.x >> 16), g2 = bf2f(gw.y & 0xffffu), g3 = bf2f(gw.y >> 16);
;             const f32x4 v = acc[ei][tk] * rstd[tk] * w4;
;             float y0 = v[0] * siluf(g0), y1 = v[1] * siluf(g1), y2 = v[2] * siluf(g2), y3 = v[3] * siluf(g3);
;     ...
;             if (!(fabsf(y0) < 1e30f)) y0 = 0.f; if (!(fabsf(y1) < 1e30f)) y1 = 0.f; if (!(fabsf(y2) < 1e30f)) y2 = 0.f; if (!(fabsf(y3) < 1e30f)) y3 = 0.f;
;     ...
;             u32x2 o; o.x = pk2(y0, y1); o.y = pk2(y2, y3);
;             *(u32x2*)(Y + row * LDY + ycol + e0) = o; } }
;     BSYNC();
	v_add_f32_e32 v31, 1.0, v31
	v_add_f32_e32 v32, 1.0, v32
	v_add_f32_e32 v33, 1.0, v33
	v_rcp_f32_e32 v30, v30
	v_rcp_f32_e32 v31, v31
	v_rcp_f32_e32 v32, v32
	v_rcp_f32_e32 v33, v33
	v_mul_f32_e32 v28, v30, v28
	v_mul_f32_e32 v24, v31, v24
	v_mul_f32_e32 v29, v32, v29
	v_mul_f32_e32 v25, v33, v25
	v_mul_f32_e32 v18, v18, v28
	v_mul_f32_e32 v19, v19, v24
	v_mul_f32_e32 v20, v20, v29
	v_mul_f32_e32 v21, v21, v25
	v_cvt_pk_bf16_f32 v18, v18, v19
	v_cvt_pk_bf16_f32 v19, v20, v21
	v_lshl_add_u64 v[26:27], v[80:81], 0, v[22:23]
	global_store_dwordx2 v[54:55], v[18:19], off offset:64
	v_lshlrev_b32_e32 v16, 16, v154
	v_and_b32_e32 v24, 0xffff0000, v154
	v_lshlrev_b32_e32 v28, 16, v155
	v_and_b32_e32 v25, 0xffff0000, v155
	v_mul_f32_e32 v29, 0xbfb8aa3b, v16
	v_mul_f32_e32 v30, 0xbfb8aa3b, v24
	v_mul_f32_e32 v31, 0xbfb8aa3b, v28
	v_mul_f32_e32 v32, 0xbfb8aa3b, v25
	v_exp_f32_e32 v29, v29
	v_exp_f32_e32 v30, v30
	v_exp_f32_e32 v31, v31
	v_exp_f32_e32 v32, v32
	v_add_f32_e32 v29, 1.0, v29
	v_add_f32_e32 v30, 1.0, v30
	v_add_f32_e32 v31, 1.0, v31
	v_add_f32_e32 v32, 1.0, v32
	v_rcp_f32_e32 v29, v29
	v_rcp_f32_e32 v30, v30
	v_rcp_f32_e32 v31, v31
	v_rcp_f32_e32 v32, v32
	v_pk_mul_f32 v[12:13], v[12:13], v[172:173]
	v_mul_f32_e32 v16, v29, v16
	v_mul_f32_e32 v24, v30, v24
	v_pk_mul_f32 v[14:15], v[14:15], v[174:175]
	v_mul_f32_e32 v28, v31, v28
	v_mul_f32_e32 v25, v32, v25
	v_mul_f32_e32 v12, v12, v16
	v_mul_f32_e32 v13, v13, v24
	v_mul_f32_e32 v14, v14, v28
	v_mul_f32_e32 v15, v15, v25
	v_cvt_pk_bf16_f32 v12, v12, v13
	v_cvt_pk_bf16_f32 v13, v14, v15
	global_store_dwordx2 v[78:79], v[12:13], off offset:96
	v_pk_mul_f32 v[8:9], v[8:9], v[172:173]
	v_pk_mul_f32 v[10:11], v[10:11], v[174:175]
	v_lshl_add_u64 v[14:15], v[68:69], 0, v[22:23]
	v_pk_mul_f32 v[4:5], v[4:5], v[172:173]
	v_pk_mul_f32 v[6:7], v[6:7], v[174:175]
	v_pk_mul_f32 v[0:1], v[0:1], v[172:173]
	v_pk_mul_f32 v[2:3], v[2:3], v[174:175]
	v_lshlrev_b32_e32 v16, 16, v158
	v_and_b32_e32 v12, 0xffff0000, v158
	v_lshlrev_b32_e32 v24, 16, v159
	v_and_b32_e32 v13, 0xffff0000, v159
	v_mul_f32_e32 v25, 0xbfb8aa3b, v16
	v_mul_f32_e32 v26, 0xbfb8aa3b, v12
	v_mul_f32_e32 v27, 0xbfb8aa3b, v24
	v_mul_f32_e32 v28, 0xbfb8aa3b, v13
	v_exp_f32_e32 v25, v25
	v_exp_f32_e32 v26, v26
	v_exp_f32_e32 v27, v27
	v_exp_f32_e32 v28, v28
	v_add_f32_e32 v25, 1.0, v25
	v_add_f32_e32 v26, 1.0, v26
	v_add_f32_e32 v27, 1.0, v27
	v_add_f32_e32 v28, 1.0, v28
	v_rcp_f32_e32 v25, v25
	v_rcp_f32_e32 v26, v26
	v_rcp_f32_e32 v27, v27
	v_rcp_f32_e32 v28, v28
	v_mul_f32_e32 v16, v25, v16
	v_mul_f32_e32 v12, v26, v12
	v_mul_f32_e32 v24, v27, v24
	v_mul_f32_e32 v13, v28, v13
	v_mul_f32_e32 v8, v8, v16
	v_mul_f32_e32 v9, v9, v12
	v_mul_f32_e32 v10, v10, v24
	v_mul_f32_e32 v11, v11, v13
	v_cvt_pk_bf16_f32 v8, v8, v9
	v_cvt_pk_bf16_f32 v9, v10, v11
	global_store_dwordx2 v[66:67], v[8:9], off offset:96
	v_lshl_add_u64 v[10:11], v[60:61], 0, v[22:23]
	v_lshlrev_b32_e32 v12, 16, v166
	v_and_b32_e32 v8, 0xffff0000, v166
	v_lshlrev_b32_e32 v13, 16, v167
	v_and_b32_e32 v9, 0xffff0000, v167
	v_mul_f32_e32 v14, 0xbfb8aa3b, v12
	v_mul_f32_e32 v15, 0xbfb8aa3b, v8
	v_mul_f32_e32 v16, 0xbfb8aa3b, v13
	v_mul_f32_e32 v22, 0xbfb8aa3b, v9
	v_exp_f32_e32 v14, v14
	v_exp_f32_e32 v15, v15
	v_exp_f32_e32 v16, v16
	v_exp_f32_e32 v22, v22
	v_add_f32_e32 v14, 1.0, v14
	v_add_f32_e32 v15, 1.0, v15
	v_add_f32_e32 v16, 1.0, v16
	v_add_f32_e32 v22, 1.0, v22
	v_rcp_f32_e32 v14, v14
	v_rcp_f32_e32 v15, v15
	v_rcp_f32_e32 v16, v16
	v_rcp_f32_e32 v22, v22
	v_mul_f32_e32 v12, v14, v12
	v_mul_f32_e32 v8, v15, v8
	v_mul_f32_e32 v13, v16, v13
	v_mul_f32_e32 v9, v22, v9
	v_mul_f32_e32 v4, v4, v12
	v_mul_f32_e32 v5, v5, v8
	v_mul_f32_e32 v6, v6, v13
	v_mul_f32_e32 v7, v7, v9
	v_cvt_pk_bf16_f32 v4, v4, v5
	v_cvt_pk_bf16_f32 v5, v6, v7
	global_store_dwordx2 v[58:59], v[4:5], off offset:96
	v_lshlrev_b32_e32 v6, 16, v178
	v_and_b32_e32 v4, 0xffff0000, v178
	v_lshlrev_b32_e32 v7, 16, v179
	v_and_b32_e32 v5, 0xffff0000, v179
	v_mul_f32_e32 v8, 0xbfb8aa3b, v6
	v_mul_f32_e32 v9, 0xbfb8aa3b, v4
	v_mul_f32_e32 v10, 0xbfb8aa3b, v7
	v_mul_f32_e32 v11, 0xbfb8aa3b, v5
	v_exp_f32_e32 v8, v8
	v_exp_f32_e32 v9, v9
	v_exp_f32_e32 v10, v10
	v_exp_f32_e32 v11, v11
	v_add_f32_e32 v8, 1.0, v8
	v_add_f32_e32 v9, 1.0, v9
	v_add_f32_e32 v10, 1.0, v10
	v_add_f32_e32 v11, 1.0, v11
	v_rcp_f32_e32 v8, v8
	v_rcp_f32_e32 v9, v9
	v_rcp_f32_e32 v10, v10
	v_rcp_f32_e32 v11, v11
	v_mul_f32_e32 v6, v8, v6
	v_mul_f32_e32 v4, v9, v4
	v_mul_f32_e32 v7, v10, v7
	v_mul_f32_e32 v5, v11, v5
	v_mul_f32_e32 v0, v0, v6
	v_mul_f32_e32 v1, v1, v4
	v_mul_f32_e32 v2, v2, v7
	v_mul_f32_e32 v3, v3, v5
	v_cvt_pk_bf16_f32 v0, v0, v1
	v_cvt_pk_bf16_f32 v1, v2, v3
	global_store_dwordx2 v[54:55], v[0:1], off offset:96
	v_mov_b32_e32 v18, v172
	v_mov_b32_e32 v19, v173
	v_mov_b32_e32 v20, v174
	v_mov_b32_e32 v21, v175
	v_mov_b32_e32 v34, v128
	v_mov_b32_e32 v35, v129
	v_mov_b32_e32 v36, v130
	v_mov_b32_e32 v37, v131
	v_mov_b32_e32 v50, v232
	v_mov_b32_e32 v51, v233
	v_mov_b32_e32 v52, v234
	v_mov_b32_e32 v53, v235
	v_mov_b32_e32 v110, v214
	v_mov_b32_e32 v111, v215
	s_waitcnt vmcnt(0) lgkmcnt(0)
	s_barrier
	s_cbranch_scc0 .LBB0_853

; __device__ __forceinline__ float logsig(float x) { return fminf(x, 0.f) - __logf(1.0f + __expf(-fabsf(x))); }
; template <int TY> __device__ __forceinline__ void sample_item(const Params& p, ldsp lds, int item) {
;     ...
;     if (tid < DK) { const int d = tid;
;         float w2[16]; float bias = 0.f, lbv = 0.f, lng = 0.f;
;         if (TY == 0) {
; #pragma unroll
;             for (int r = 0; r < 16; ++r) w2[r] = p.in[10][r * 256 + h * 64 + d];
;             bias = p.in[11][h * 64 + d];
;         } else if (TY == 1) { const float t0 = p.in[13][h * 128 + d], t1 = p.in[13][512 + h * 128 + d], t2 = p.in[13][1024 + h * 128 + d];
;             const float mx = fmaxf(t0, fmaxf(t1, t2)); const float e0 = __expf(t0 - mx), e1 = __expf(t1 - mx), e2 = __expf(t2 - mx); lbv = e0 / (e0 + e1 + e2);
;         } else lng = __logf(1.0f - exp2f(-5.0f - (float)h));
;         float run = 0.f; float bt[8], qv[8], kv[8];
; #pragma unroll
;         for (int t = 0; t < 8; ++t) { float g;
;             if (TY == 0) { float x = bias;
; #pragma unroll
;                 for (int r = 0; r < 16; ++r) x += bf2f(Pb[(size_t)t * NE + E_LR + r]) * w2[r];
;                 g = logsig(x) * 0.0625f; qv[t] = bf2f(Pb[(size_t)t * NE + E_QA + h * 64 + d]) * 0.125f; kv[t] = bf2f(Pb[(size_t)t * NE + E_KA + h * 64 + d]);
.LBB0_1024:
	s_or_b64 exec, exec, s[0:1]
	v_cmp_gt_i32_e64 s[10:11], 64, v0
	v_ashrrev_i32_e32 v1, 31, v0
	s_and_saveexec_b64 s[8:9], s[10:11]
	s_cbranch_execz .LBB0_1026
	v_lshl_add_u32 v2, s38, 6, v0
	v_readlane_b32 s76, v252, 20
	v_ashrrev_i32_e32 v3, 31, v2
	v_readlane_b32 s77, v252, 21
	v_readlane_b32 s78, v252, 22
	v_readlane_b32 s79, v252, 23
	v_readlane_b32 s80, v252, 24
	v_readlane_b32 s81, v252, 25
	v_readlane_b32 s82, v252, 26
	v_readlane_b32 s83, v252, 27
	v_readlane_b32 s84, v252, 28
	v_readlane_b32 s85, v252, 29
	v_lshlrev_b64 v[2:3], 2, v[2:3]
	v_readlane_b32 s86, v252, 30
	v_readlane_b32 s87, v252, 31
	v_readlane_b32 s88, v252, 32
	v_readlane_b32 s89, v252, 33
	s_mov_b64 s[76:77], s[80:81]
	v_lshl_add_u64 v[6:7], s[76:77], 0, v[2:3]
	v_add_co_u32_e32 v8, vcc, 0x1000, v6
	s_movk_i32 s18, 0x2000
	s_nop 0
	v_addc_co_u32_e32 v9, vcc, 0, v7, vcc
	global_load_dword v28, v[6:7], off
	global_load_dword v26, v[6:7], off offset:1024
	global_load_dword v24, v[6:7], off offset:2048
	global_load_dword v22, v[6:7], off offset:3072
	global_load_dword v27, v[8:9], off
	global_load_dword v25, v[8:9], off offset:1024
	global_load_dword v23, v[8:9], off offset:2048
	global_load_dword v21, v[8:9], off offset:3072
	v_add_co_u32_e32 v8, vcc, s18, v6
	s_mov_b64 s[78:79], s[82:83]
	s_nop 0
	v_addc_co_u32_e32 v9, vcc, 0, v7, vcc
	v_add_co_u32_e32 v6, vcc, s56, v6
	v_mov_b32_e32 v5, 0x1000
	s_nop 0
	v_addc_co_u32_e32 v7, vcc, 0, v7, vcc
	global_load_dword v20, v[6:7], off offset:-4096
	global_load_dword v19, v[8:9], off offset:1024
	global_load_dword v18, v[8:9], off offset:2048
	global_load_dword v16, v[8:9], off offset:3072
	global_load_dword v15, v[6:7], off
	global_load_dword v14, v[6:7], off offset:1024
	global_load_dword v13, v[6:7], off offset:2048
	global_load_dword v11, v[6:7], off offset:3072
	v_lshl_add_u64 v[2:3], s[78:79], 0, v[2:3]
	global_load_dwordx4 v[6:9], v5, s[16:17] offset:3072
	global_load_dword v12, v[2:3], off
	v_mov_b32_e32 v10, 0x3000
	global_load_dwordx4 v[30:33], v10, s[16:17] offset:2560
	s_mov_b32 s19, 0xbfb8aa3b
	s_mov_b32 s38, 0x3f317217
	s_mov_b32 s39, 0x7f800000
	v_mov_b32_e32 v34, 0x5000
	v_mov_b32_e32 v37, 0x7000
	v_mov_b32_e32 v40, 0x9000
	v_mov_b32_e32 v43, 0xb000
	v_mov_b32_e32 v46, 0xd000
	v_mov_b32_e32 v49, 0xe000
	v_readlane_b32 s90, v252, 34
	v_readlane_b32 s91, v252, 35
	s_mov_b64 s[80:81], s[84:85]
	s_mov_b64 s[82:83], s[86:87]
	s_mov_b64 s[84:85], s[88:89]
	s_waitcnt vmcnt(0)
	v_lshlrev_b32_e32 v2, 16, v6
	v_fma_f32 v2, v28, v2, v12
	v_and_b32_e32 v3, 0xffff0000, v6
	v_fmac_f32_e32 v2, v26, v3
	v_lshlrev_b32_e32 v3, 16, v7
	v_fmac_f32_e32 v2, v24, v3
	v_and_b32_e32 v3, 0xffff0000, v7
	v_fmac_f32_e32 v2, v22, v3
	v_lshlrev_b32_e32 v3, 16, v8
	v_fmac_f32_e32 v2, v27, v3
	v_and_b32_e32 v3, 0xffff0000, v8
	v_fmac_f32_e32 v2, v25, v3
	v_lshlrev_b32_e32 v3, 16, v9
	v_fmac_f32_e32 v2, v23, v3
	v_and_b32_e32 v3, 0xffff0000, v9
	global_load_dwordx4 v[6:9], v5, s[16:17] offset:3088
	v_fmac_f32_e32 v2, v21, v3
	s_waitcnt vmcnt(0)
	v_lshlrev_b32_e32 v3, 16, v6
	v_fmac_f32_e32 v2, v20, v3
	v_and_b32_e32 v3, 0xffff0000, v6
	v_fmac_f32_e32 v2, v19, v3
	v_lshlrev_b32_e32 v3, 16, v7
	v_fmac_f32_e32 v2, v18, v3
	v_and_b32_e32 v3, 0xffff0000, v7
	v_fmac_f32_e32 v2, v16, v3
	v_lshlrev_b32_e32 v3, 16, v8
	v_fmac_f32_e32 v2, v15, v3
	v_and_b32_e32 v3, 0xffff0000, v8
	v_fmac_f32_e32 v2, v14, v3
	v_lshlrev_b32_e32 v3, 16, v9
	v_fmac_f32_e32 v2, v13, v3
	v_and_b32_e32 v3, 0xffff0000, v9
	v_fmac_f32_e32 v2, v11, v3
	v_min_f32_e32 v3, 0, v2
	v_mul_f32_e64 v2, |v2|, s19
	v_exp_f32_e32 v2, v2
	v_lshlrev_b32_e32 v8, 16, v30
	v_fma_f32 v8, v28, v8, v12
	v_and_b32_e32 v9, 0xffff0000, v30
	v_add_f32_e32 v2, 1.0, v2
	v_cmp_gt_f32_e32 vcc, s33, v2
	v_fmac_f32_e32 v8, v26, v9
	v_lshlrev_b32_e32 v9, 16, v31
	v_cndmask_b32_e64 v5, 0, 32, vcc
	v_ldexp_f32 v2, v2, v5
	v_log_f32_e32 v2, v2
	v_fmac_f32_e32 v8, v24, v9
	v_and_b32_e32 v9, 0xffff0000, v31
	v_fmac_f32_e32 v8, v22, v9
	v_mul_f32_e32 v5, 0x3f317217, v2
	v_fma_f32 v5, v2, s38, -v5
	v_fmac_f32_e32 v5, 0x3377d1cf, v2
	v_fmac_f32_e32 v5, 0x3f317217, v2
	v_cmp_lt_f32_e64 s[0:1], |v2|, s39
	v_lshlrev_b32_e32 v9, 16, v32
	v_fmac_f32_e32 v8, v27, v9
	v_cndmask_b32_e64 v2, v2, v5, s[0:1]
	v_cndmask_b32_e32 v5, 0, v185, vcc
	s_add_u32 s0, s16, s37
	v_sub_f32_e32 v2, v2, v5
	s_addc_u32 s1, s17, 0
	v_and_b32_e32 v9, 0xffff0000, v32
	v_sub_f32_e32 v6, v3, v2
	v_lshl_add_u64 v[2:3], v[0:1], 1, s[0:1]
	s_mov_b64 s[98:99], s[0:1]
	v_lshlrev_b32_e32 v144, 1, v0
	v_add_u32_e32 v145, 0x1e00, v144
	v_add_u32_e32 v146, 0x3c00, v144
	v_add_u32_e32 v147, 0x5a00, v144
	v_add_u32_e32 v148, 0x7800, v144
	v_add_u32_e32 v149, 0x9600, v144
	v_add_u32_e32 v150, 0xb400, v144
	v_add_u32_e32 v151, 0xd200, v144
	global_load_ushort v186, v144, s[98:99]
	global_load_dwordx4 v[188:191], v10, s[16:17] offset:2576
	global_load_ushort v187, v144, s[98:99] offset:512
	global_load_ushort v192, v145, s[98:99]
	global_load_ushort v193, v145, s[98:99] offset:512
	global_load_dwordx4 v[194:197], v34, s[16:17] offset:2048
	global_load_dwordx4 v[198:201], v34, s[16:17] offset:2064
	global_load_ushort v202, v146, s[98:99]
	global_load_ushort v203, v146, s[98:99] offset:512
	global_load_dwordx4 v[204:207], v37, s[16:17] offset:1536
	global_load_dwordx4 v[208:211], v37, s[16:17] offset:1552
	global_load_dwordx4 v[212:215], v40, s[16:17] offset:1024
	global_load_ushort v216, v147, s[98:99]
	global_load_ushort v217, v147, s[98:99] offset:512
	global_load_dwordx4 v[218:221], v40, s[16:17] offset:1040
	global_load_ushort v222, v148, s[98:99]
	global_load_ushort v223, v148, s[98:99] offset:512
	global_load_dwordx4 v[224:227], v43, s[16:17] offset:512
	global_load_dwordx4 v[228:231], v43, s[16:17] offset:528
	global_load_dwordx4 v[232:235], v46, s[16:17]
	global_load_ushort v236, v149, s[98:99]
	global_load_ushort v237, v149, s[98:99] offset:512
	global_load_dwordx4 v[238:241], v46, s[16:17] offset:16
	global_load_ushort v242, v150, s[98:99]
	global_load_ushort v243, v150, s[98:99] offset:512
	global_load_dwordx4 v[244:247], v49, s[16:17] offset:3584
	global_load_dwordx4 v[152:155], v49, s[16:17] offset:3600
	global_load_ushort v248, v151, s[98:99]
	global_load_ushort v249, v151, s[98:99] offset:512
	v_fmac_f32_e32 v8, v25, v9
	v_lshlrev_b32_e32 v9, 16, v33
	v_fmac_f32_e32 v8, v23, v9
	v_and_b32_e32 v9, 0xffff0000, v33
	v_fmac_f32_e32 v8, v21, v9
	s_mov_b32 s0, 0x3d800000
	v_fma_f32 v6, v6, s0, 0
	s_waitcnt vmcnt(0)
; __device__ __forceinline__ float siluf(float x) { return x * __builtin_amdgcn_rcpf(1.0f + __expf(-x)); }
; __device__ __forceinline__ float logsig(float x) { return fminf(x, 0.f) - __logf(1.0f + __expf(-fabsf(x))); }
; template <int TY> __device__ __forceinline__ void sample_item(const Params& p, ldsp lds, int item) {
;     ...
;         for (int t = 0; t < 8; ++t) { float g;
;             if (TY == 0) { float x = bias;
; #pragma unroll
;                 for (int r = 0; r < 16; ++r) x += bf2f(Pb[(size_t)t * NE + E_LR + r]) * w2[r];
;                 g = logsig(x) * 0.0625f; qv[t] = bf2f(Pb[(size_t)t * NE + E_QA + h * 64 + d]) * 0.125f; kv[t] = bf2f(Pb[(size_t)t * NE + E_KA + h * 64 + d]);
;             } else if (TY == 1) { const float xf = bf2f(Pb[(size_t)t * NE + E_FB + h * 128 + d]); const float sig = __builtin_amdgcn_rcpf(1.0f + __expf(-xf));
;                 g = __logf(lbv + (1.0f - lbv) * sig); kv[t] = (1.0f - lbv) * __builtin_amdgcn_rcpf(1.0f + __expf(xf)); qv[t] = siluf(bf2f(Pb[(size_t)t * NE + E_QB + h * 128 + d]));
;             } else { g = lng; qv[t] = bf2f(Pb[(size_t)t * NO + O_Q + h * 256 + d]); kv[t] = bf2f(Pb[(size_t)t * NO + O_K + h * 256 + d]); }
;             run += g; bt[t] = run; }
	v_lshlrev_b32_e32 v5, 16, v186
	v_mul_f32_e32 v7, 0x3e000000, v5
	v_lshlrev_b32_e32 v9, 16, v188
	v_fmac_f32_e32 v8, v20, v9
	v_and_b32_e32 v9, 0xffff0000, v188
	v_fmac_f32_e32 v8, v19, v9
	v_lshlrev_b32_e32 v9, 16, v189
	v_fmac_f32_e32 v8, v18, v9
	v_and_b32_e32 v9, 0xffff0000, v189
	v_fmac_f32_e32 v8, v16, v9
	v_lshlrev_b32_e32 v9, 16, v190
	v_fmac_f32_e32 v8, v15, v9
	v_and_b32_e32 v9, 0xffff0000, v190
	v_fmac_f32_e32 v8, v14, v9
	v_lshlrev_b32_e32 v9, 16, v191
	v_fmac_f32_e32 v8, v13, v9
	v_and_b32_e32 v9, 0xffff0000, v191
	v_fmac_f32_e32 v8, v11, v9
	v_min_f32_e32 v9, 0, v8
	v_mul_f32_e64 v8, |v8|, s19
	v_exp_f32_e32 v8, v8
	s_nop 0
	v_add_f32_e32 v8, 1.0, v8
	v_cmp_gt_f32_e32 vcc, s33, v8
	s_nop 1
	v_cndmask_b32_e64 v10, 0, 32, vcc
	v_ldexp_f32 v8, v8, v10
	v_log_f32_e32 v8, v8
	s_nop 0
	v_mul_f32_e32 v10, 0x3f317217, v8
	v_fma_f32 v10, v8, s38, -v10
	v_fmac_f32_e32 v10, 0x3377d1cf, v8
	v_fmac_f32_e32 v10, 0x3f317217, v8
	v_cmp_lt_f32_e64 s[0:1], |v8|, s39
	s_nop 1
	v_cndmask_b32_e64 v8, v8, v10, s[0:1]
	v_cndmask_b32_e32 v10, 0, v185, vcc
	v_sub_f32_e32 v8, v8, v10
	v_sub_f32_e32 v29, v9, v8
	v_add_co_u32_e32 v8, vcc, s57, v2
	s_nop 1
	v_addc_co_u32_e32 v9, vcc, 0, v3, vcc
	v_lshlrev_b32_e32 v8, 16, v192
	v_mul_f32_e32 v10, 0x3e000000, v8
	v_add_co_u32_e32 v8, vcc, s18, v2
	s_nop 1
	v_addc_co_u32_e32 v9, vcc, 0, v3, vcc
	v_fmamk_f32 v9, v29, 0x3d800000, v6
	v_lshlrev_b32_e32 v5, 16, v187
	v_lshlrev_b32_e32 v8, 16, v193
	v_lshlrev_b32_e32 v29, 16, v194
	v_fma_f32 v29, v28, v29, v12
	v_and_b32_e32 v30, 0xffff0000, v194
	v_fmac_f32_e32 v29, v26, v30
	v_lshlrev_b32_e32 v30, 16, v195
	v_fmac_f32_e32 v29, v24, v30
	v_and_b32_e32 v30, 0xffff0000, v195
	v_fmac_f32_e32 v29, v22, v30
	v_lshlrev_b32_e32 v30, 16, v196
	v_fmac_f32_e32 v29, v27, v30
	v_and_b32_e32 v30, 0xffff0000, v196
	v_fmac_f32_e32 v29, v25, v30
	v_lshlrev_b32_e32 v30, 16, v197
	v_fmac_f32_e32 v29, v23, v30
	v_and_b32_e32 v30, 0xffff0000, v197
	v_fmac_f32_e32 v29, v21, v30
	v_lshlrev_b32_e32 v34, 16, v198
	v_fmac_f32_e32 v29, v20, v34
	v_and_b32_e32 v30, 0xffff0000, v198
	v_fmac_f32_e32 v29, v19, v30
	v_lshlrev_b32_e32 v30, 16, v199
	v_fmac_f32_e32 v29, v18, v30
	v_and_b32_e32 v30, 0xffff0000, v199
	v_fmac_f32_e32 v29, v16, v30
	v_lshlrev_b32_e32 v30, 16, v200
	v_fmac_f32_e32 v29, v15, v30
	v_and_b32_e32 v30, 0xffff0000, v200
	v_fmac_f32_e32 v29, v14, v30
	v_lshlrev_b32_e32 v30, 16, v201
	v_fmac_f32_e32 v29, v13, v30
	v_and_b32_e32 v30, 0xffff0000, v201
	v_fmac_f32_e32 v29, v11, v30
	v_min_f32_e32 v30, 0, v29
	v_mul_f32_e64 v29, |v29|, s19
	v_exp_f32_e32 v29, v29
	s_nop 0
	v_add_f32_e32 v29, 1.0, v29
	v_cmp_gt_f32_e32 vcc, s33, v29
	s_nop 1
	v_cndmask_b32_e64 v31, 0, 32, vcc
	v_ldexp_f32 v29, v29, v31
	v_log_f32_e32 v29, v29
	s_nop 0
	v_mul_f32_e32 v31, 0x3f317217, v29
	v_fma_f32 v31, v29, s38, -v31
	v_fmac_f32_e32 v31, 0x3377d1cf, v29
	v_fmac_f32_e32 v31, 0x3f317217, v29
	v_cmp_lt_f32_e64 s[0:1], |v29|, s39
	s_nop 1
	v_cndmask_b32_e64 v29, v29, v31, s[0:1]
	v_cndmask_b32_e32 v31, 0, v185, vcc
	v_add_co_u32_e32 v32, vcc, s56, v2
	v_sub_f32_e32 v29, v29, v31
	s_nop 0
	v_addc_co_u32_e32 v33, vcc, 0, v3, vcc
	v_sub_f32_e32 v30, v30, v29
	v_fmamk_f32 v30, v30, 0x3d800000, v9
	v_lshlrev_b32_e32 v29, 16, v202
	v_mul_f32_e32 v31, 0x3e000000, v29
	v_lshlrev_b32_e32 v29, 16, v203
	v_lshlrev_b32_e32 v36, 16, v204
	v_fma_f32 v36, v28, v36, v12
	v_and_b32_e32 v32, 0xffff0000, v204
	v_fmac_f32_e32 v36, v26, v32
	v_lshlrev_b32_e32 v32, 16, v205
	v_fmac_f32_e32 v36, v24, v32
	v_and_b32_e32 v32, 0xffff0000, v205
	v_fmac_f32_e32 v36, v22, v32
	v_lshlrev_b32_e32 v32, 16, v206
	v_fmac_f32_e32 v36, v27, v32
	v_and_b32_e32 v32, 0xffff0000, v206
	v_fmac_f32_e32 v36, v25, v32
	v_lshlrev_b32_e32 v32, 16, v207
	v_fmac_f32_e32 v36, v23, v32
	v_and_b32_e32 v32, 0xffff0000, v207
	v_fmac_f32_e32 v36, v21, v32
	v_lshlrev_b32_e32 v37, 16, v208
	v_fmac_f32_e32 v36, v20, v37
	v_and_b32_e32 v32, 0xffff0000, v208
	v_fmac_f32_e32 v36, v19, v32
	v_lshlrev_b32_e32 v32, 16, v209
	v_fmac_f32_e32 v36, v18, v32
	v_and_b32_e32 v32, 0xffff0000, v209
	v_fmac_f32_e32 v36, v16, v32
	v_lshlrev_b32_e32 v32, 16, v210
	v_fmac_f32_e32 v36, v15, v32
	v_and_b32_e32 v32, 0xffff0000, v210
	v_fmac_f32_e32 v36, v14, v32
	v_lshlrev_b32_e32 v32, 16, v211
	v_fmac_f32_e32 v36, v13, v32
	v_and_b32_e32 v32, 0xffff0000, v211
	v_fmac_f32_e32 v36, v11, v32
	v_mul_f32_e64 v33, |v36|, s19
	v_exp_f32_e32 v33, v33
	v_min_f32_e32 v32, 0, v36
	v_add_f32_e32 v33, 1.0, v33
	v_cmp_gt_f32_e32 vcc, s33, v33
	s_nop 1
	v_cndmask_b32_e64 v34, 0, 32, vcc
	v_ldexp_f32 v33, v33, v34
	v_log_f32_e32 v33, v33
	s_nop 0
	v_mul_f32_e32 v34, 0x3f317217, v33
	v_fma_f32 v34, v33, s38, -v34
	v_fmac_f32_e32 v34, 0x3377d1cf, v33
	v_fmac_f32_e32 v34, 0x3f317217, v33
	v_cmp_lt_f32_e64 s[0:1], |v33|, s39
	s_nop 1
	v_cndmask_b32_e64 v33, v33, v34, s[0:1]
	v_cndmask_b32_e32 v34, 0, v185, vcc
	v_sub_f32_e32 v33, v33, v34
	s_movk_i32 s0, 0x5000
	v_sub_f32_e32 v35, v32, v33
	v_add_co_u32_e32 v32, vcc, s0, v2
	s_nop 1
	v_addc_co_u32_e32 v33, vcc, 0, v3, vcc
	v_lshlrev_b32_e32 v34, 16, v216
	v_fmamk_f32 v33, v35, 0x3d800000, v30
	v_lshlrev_b32_e32 v35, 16, v212
	v_fma_f32 v35, v28, v35, v12
	v_and_b32_e32 v36, 0xffff0000, v212
	v_fmac_f32_e32 v35, v26, v36
	v_lshlrev_b32_e32 v36, 16, v213
	v_fmac_f32_e32 v35, v24, v36
	v_and_b32_e32 v36, 0xffff0000, v213
	v_fmac_f32_e32 v35, v22, v36
	v_lshlrev_b32_e32 v36, 16, v214
	v_fmac_f32_e32 v35, v27, v36
	v_and_b32_e32 v36, 0xffff0000, v214
	v_fmac_f32_e32 v35, v25, v36
	v_lshlrev_b32_e32 v36, 16, v215
	v_fmac_f32_e32 v35, v23, v36
	v_and_b32_e32 v36, 0xffff0000, v215
	v_fmac_f32_e32 v35, v21, v36
	v_mul_f32_e32 v34, 0x3e000000, v34
; __device__ __forceinline__ float siluf(float x) { return x * __builtin_amdgcn_rcpf(1.0f + __expf(-x)); }
; __device__ __forceinline__ float logsig(float x) { return fminf(x, 0.f) - __logf(1.0f + __expf(-fabsf(x))); }
; template <int TY> __device__ __forceinline__ void sample_item(const Params& p, ldsp lds, int item) {
;     ...
;         for (int t = 0; t < 8; ++t) { float g;
;             if (TY == 0) { float x = bias;
; #pragma unroll
;                 for (int r = 0; r < 16; ++r) x += bf2f(Pb[(size_t)t * NE + E_LR + r]) * w2[r];
;                 g = logsig(x) * 0.0625f; qv[t] = bf2f(Pb[(size_t)t * NE + E_QA + h * 64 + d]) * 0.125f; kv[t] = bf2f(Pb[(size_t)t * NE + E_KA + h * 64 + d]);
;             } else if (TY == 1) { const float xf = bf2f(Pb[(size_t)t * NE + E_FB + h * 128 + d]); const float sig = __builtin_amdgcn_rcpf(1.0f + __expf(-xf));
;                 g = __logf(lbv + (1.0f - lbv) * sig); kv[t] = (1.0f - lbv) * __builtin_amdgcn_rcpf(1.0f + __expf(xf)); qv[t] = siluf(bf2f(Pb[(size_t)t * NE + E_QB + h * 128 + d]));
;             } else { g = lng; qv[t] = bf2f(Pb[(size_t)t * NO + O_Q + h * 256 + d]); kv[t] = bf2f(Pb[(size_t)t * NO + O_K + h * 256 + d]); }
;             run += g; bt[t] = run; }
	v_lshlrev_b32_e32 v32, 16, v217
	v_lshlrev_b32_e32 v40, 16, v218
	v_fmac_f32_e32 v35, v20, v40
	v_and_b32_e32 v36, 0xffff0000, v218
	v_fmac_f32_e32 v35, v19, v36
	v_lshlrev_b32_e32 v36, 16, v219
	v_fmac_f32_e32 v35, v18, v36
	v_and_b32_e32 v36, 0xffff0000, v219
	v_fmac_f32_e32 v35, v16, v36
	v_lshlrev_b32_e32 v36, 16, v220
	v_fmac_f32_e32 v35, v15, v36
	v_and_b32_e32 v36, 0xffff0000, v220
	v_fmac_f32_e32 v35, v14, v36
	v_lshlrev_b32_e32 v36, 16, v221
	v_fmac_f32_e32 v35, v13, v36
	v_and_b32_e32 v36, 0xffff0000, v221
	v_fmac_f32_e32 v35, v11, v36
	v_min_f32_e32 v36, 0, v35
	v_mul_f32_e64 v35, |v35|, s19
	v_exp_f32_e32 v35, v35
	s_nop 0
	v_add_f32_e32 v35, 1.0, v35
	v_cmp_gt_f32_e32 vcc, s33, v35
	s_nop 1
	v_cndmask_b32_e64 v37, 0, 32, vcc
	v_ldexp_f32 v35, v35, v37
	v_log_f32_e32 v35, v35
	s_nop 0
	v_mul_f32_e32 v37, 0x3f317217, v35
	v_fma_f32 v37, v35, s38, -v37
	v_fmac_f32_e32 v37, 0x3377d1cf, v35
	v_fmac_f32_e32 v37, 0x3f317217, v35
	v_cmp_lt_f32_e64 s[0:1], |v35|, s39
	s_nop 1
	v_cndmask_b32_e64 v35, v35, v37, s[0:1]
	s_movk_i32 s0, 0x7000
	v_cndmask_b32_e32 v37, 0, v185, vcc
	v_add_co_u32_e32 v38, vcc, s0, v2
	v_sub_f32_e32 v35, v35, v37
	s_nop 0
	v_addc_co_u32_e32 v39, vcc, 0, v3, vcc
	v_sub_f32_e32 v36, v36, v35
	v_fmamk_f32 v36, v36, 0x3d800000, v33
	v_lshlrev_b32_e32 v35, 16, v222
	v_mul_f32_e32 v37, 0x3e000000, v35
	v_lshlrev_b32_e32 v35, 16, v223
	v_lshlrev_b32_e32 v42, 16, v224
	v_fma_f32 v42, v28, v42, v12
	v_and_b32_e32 v38, 0xffff0000, v224
	v_fmac_f32_e32 v42, v26, v38
	v_lshlrev_b32_e32 v38, 16, v225
	v_fmac_f32_e32 v42, v24, v38
	v_and_b32_e32 v38, 0xffff0000, v225
	v_fmac_f32_e32 v42, v22, v38
	v_lshlrev_b32_e32 v38, 16, v226
	v_fmac_f32_e32 v42, v27, v38
	v_and_b32_e32 v38, 0xffff0000, v226
	v_fmac_f32_e32 v42, v25, v38
	v_lshlrev_b32_e32 v38, 16, v227
	v_fmac_f32_e32 v42, v23, v38
	v_and_b32_e32 v38, 0xffff0000, v227
	v_fmac_f32_e32 v42, v21, v38
	v_lshlrev_b32_e32 v43, 16, v228
	v_fmac_f32_e32 v42, v20, v43
	v_and_b32_e32 v38, 0xffff0000, v228
	v_fmac_f32_e32 v42, v19, v38
	v_lshlrev_b32_e32 v38, 16, v229
	v_fmac_f32_e32 v42, v18, v38
	v_and_b32_e32 v38, 0xffff0000, v229
	v_fmac_f32_e32 v42, v16, v38
	v_lshlrev_b32_e32 v38, 16, v230
	v_fmac_f32_e32 v42, v15, v38
	v_and_b32_e32 v38, 0xffff0000, v230
	v_fmac_f32_e32 v42, v14, v38
	v_lshlrev_b32_e32 v38, 16, v231
	v_fmac_f32_e32 v42, v13, v38
	v_and_b32_e32 v38, 0xffff0000, v231
	v_fmac_f32_e32 v42, v11, v38
	v_mul_f32_e64 v39, |v42|, s19
	v_exp_f32_e32 v39, v39
	v_min_f32_e32 v38, 0, v42
	v_add_f32_e32 v39, 1.0, v39
	v_cmp_gt_f32_e32 vcc, s33, v39
	s_nop 1
	v_cndmask_b32_e64 v40, 0, 32, vcc
	v_ldexp_f32 v39, v39, v40
	v_log_f32_e32 v39, v39
	s_nop 0
	v_mul_f32_e32 v40, 0x3f317217, v39
	v_fma_f32 v40, v39, s38, -v40
	v_fmac_f32_e32 v40, 0x3377d1cf, v39
	v_fmac_f32_e32 v40, 0x3f317217, v39
	v_cmp_lt_f32_e64 s[0:1], |v39|, s39
	s_nop 1
	v_cndmask_b32_e64 v39, v39, v40, s[0:1]
	v_cndmask_b32_e32 v40, 0, v185, vcc
	v_sub_f32_e32 v39, v39, v40
	s_mov_b32 s0, 0x9000
	v_sub_f32_e32 v41, v38, v39
	v_add_co_u32_e32 v38, vcc, s0, v2
	s_nop 1
	v_addc_co_u32_e32 v39, vcc, 0, v3, vcc
	v_lshlrev_b32_e32 v40, 16, v236
	v_fmamk_f32 v39, v41, 0x3d800000, v36
	v_lshlrev_b32_e32 v41, 16, v232
	v_fma_f32 v41, v28, v41, v12
	v_and_b32_e32 v42, 0xffff0000, v232
	v_fmac_f32_e32 v41, v26, v42
	v_lshlrev_b32_e32 v42, 16, v233
	v_fmac_f32_e32 v41, v24, v42
	v_and_b32_e32 v42, 0xffff0000, v233
	v_fmac_f32_e32 v41, v22, v42
	v_lshlrev_b32_e32 v42, 16, v234
	v_fmac_f32_e32 v41, v27, v42
	v_and_b32_e32 v42, 0xffff0000, v234
	v_fmac_f32_e32 v41, v25, v42
	v_lshlrev_b32_e32 v42, 16, v235
	v_fmac_f32_e32 v41, v23, v42
	v_and_b32_e32 v42, 0xffff0000, v235
	v_fmac_f32_e32 v41, v21, v42
	v_mul_f32_e32 v40, 0x3e000000, v40
	v_lshlrev_b32_e32 v38, 16, v237
	v_lshlrev_b32_e32 v46, 16, v238
	v_fmac_f32_e32 v41, v20, v46
	v_and_b32_e32 v42, 0xffff0000, v238
	v_fmac_f32_e32 v41, v19, v42
	v_lshlrev_b32_e32 v42, 16, v239
	v_fmac_f32_e32 v41, v18, v42
	v_and_b32_e32 v42, 0xffff0000, v239
	v_fmac_f32_e32 v41, v16, v42
	v_lshlrev_b32_e32 v42, 16, v240
	v_fmac_f32_e32 v41, v15, v42
	v_and_b32_e32 v42, 0xffff0000, v240
	v_fmac_f32_e32 v41, v14, v42
	v_lshlrev_b32_e32 v42, 16, v241
	v_fmac_f32_e32 v41, v13, v42
	v_and_b32_e32 v42, 0xffff0000, v241
	v_fmac_f32_e32 v41, v11, v42
	v_min_f32_e32 v42, 0, v41
	v_mul_f32_e64 v41, |v41|, s19
	v_exp_f32_e32 v41, v41
	s_nop 0
	v_add_f32_e32 v41, 1.0, v41
	v_cmp_gt_f32_e32 vcc, s33, v41
	s_nop 1
	v_cndmask_b32_e64 v43, 0, 32, vcc
	v_ldexp_f32 v41, v41, v43
	v_log_f32_e32 v41, v41
	s_nop 0
	v_mul_f32_e32 v43, 0x3f317217, v41
	v_fma_f32 v43, v41, s38, -v43
	v_fmac_f32_e32 v43, 0x3377d1cf, v41
	v_fmac_f32_e32 v43, 0x3f317217, v41
	v_cmp_lt_f32_e64 s[0:1], |v41|, s39
	s_nop 1
	v_cndmask_b32_e64 v41, v41, v43, s[0:1]
	s_mov_b32 s0, 0xb000
	v_cndmask_b32_e32 v43, 0, v185, vcc
	v_add_co_u32_e32 v44, vcc, s0, v2
	v_sub_f32_e32 v41, v41, v43
	s_nop 0
	v_addc_co_u32_e32 v45, vcc, 0, v3, vcc
	v_sub_f32_e32 v42, v42, v41
	v_fmamk_f32 v42, v42, 0x3d800000, v39
	v_lshlrev_b32_e32 v41, 16, v242
	v_mul_f32_e32 v43, 0x3e000000, v41
	v_lshlrev_b32_e32 v41, 16, v243
	v_lshlrev_b32_e32 v48, 16, v244
; __device__ __forceinline__ float siluf(float x) { return x * __builtin_amdgcn_rcpf(1.0f + __expf(-x)); }
; __device__ __forceinline__ float logsig(float x) { return fminf(x, 0.f) - __logf(1.0f + __expf(-fabsf(x))); }
; template <int TY> __device__ __forceinline__ void sample_item(const Params& p, ldsp lds, int item) {
;     ...
;         for (int t = 0; t < 8; ++t) { float g;
;             if (TY == 0) { float x = bias;
; #pragma unroll
;                 for (int r = 0; r < 16; ++r) x += bf2f(Pb[(size_t)t * NE + E_LR + r]) * w2[r];
;                 g = logsig(x) * 0.0625f; qv[t] = bf2f(Pb[(size_t)t * NE + E_QA + h * 64 + d]) * 0.125f; kv[t] = bf2f(Pb[(size_t)t * NE + E_KA + h * 64 + d]);
;             } else if (TY == 1) { const float xf = bf2f(Pb[(size_t)t * NE + E_FB + h * 128 + d]); const float sig = __builtin_amdgcn_rcpf(1.0f + __expf(-xf));
;                 g = __logf(lbv + (1.0f - lbv) * sig); kv[t] = (1.0f - lbv) * __builtin_amdgcn_rcpf(1.0f + __expf(xf)); qv[t] = siluf(bf2f(Pb[(size_t)t * NE + E_QB + h * 128 + d]));
;             } else { g = lng; qv[t] = bf2f(Pb[(size_t)t * NO + O_Q + h * 256 + d]); kv[t] = bf2f(Pb[(size_t)t * NO + O_K + h * 256 + d]); }
;             run += g; bt[t] = run; }
; #pragma unroll
;         for (int t = 0; t < 8; ++t) { Bs[t * DK + d] = bt[t]; QR[t * DK + d] = qv[t]; KR[t * DK + d] = kv[t];
;             QK[d * 16 + t] = qv[t] * __expf(bt[t]); QK[d * 16 + 8 + t] = kv[t] * __expf(run - bt[t]); }
;         DECs[d] = __expf(run); }
	v_fmac_f32_e32 v12, v28, v48
	v_and_b32_e32 v28, 0xffff0000, v244
	v_fmac_f32_e32 v12, v26, v28
	v_lshlrev_b32_e32 v26, 16, v245
	v_fmac_f32_e32 v12, v24, v26
	v_and_b32_e32 v24, 0xffff0000, v245
	v_fmac_f32_e32 v12, v22, v24
	v_lshlrev_b32_e32 v22, 16, v246
	v_fmac_f32_e32 v12, v27, v22
	v_and_b32_e32 v22, 0xffff0000, v246
	v_fmac_f32_e32 v12, v25, v22
	v_lshlrev_b32_e32 v22, 16, v247
	v_fmac_f32_e32 v12, v23, v22
	v_and_b32_e32 v22, 0xffff0000, v247
	v_fmac_f32_e32 v12, v21, v22
	v_lshlrev_b32_e32 v21, 16, v152
	v_fmac_f32_e32 v12, v20, v21
	v_and_b32_e32 v20, 0xffff0000, v152
	v_fmac_f32_e32 v12, v19, v20
	v_lshlrev_b32_e32 v19, 16, v153
	v_fmac_f32_e32 v12, v18, v19
	v_and_b32_e32 v18, 0xffff0000, v153
	v_fmac_f32_e32 v12, v16, v18
	v_lshlrev_b32_e32 v16, 16, v154
	v_fmac_f32_e32 v12, v15, v16
	v_and_b32_e32 v15, 0xffff0000, v154
	v_fmac_f32_e32 v12, v14, v15
	v_lshlrev_b32_e32 v14, 16, v155
	v_fmac_f32_e32 v12, v13, v14
	v_and_b32_e32 v13, 0xffff0000, v155
	v_fmac_f32_e32 v12, v11, v13
	v_min_f32_e32 v11, 0, v12
	v_mul_f32_e64 v12, |v12|, s19
	v_exp_f32_e32 v12, v12
	v_mul_f32_e32 v14, 0x3fb8aa3b, v6
	v_exp_f32_e32 v14, v14
	v_add_f32_e32 v12, 1.0, v12
	v_cmp_gt_f32_e32 vcc, s33, v12
	s_nop 1
	v_cndmask_b32_e64 v13, 0, 32, vcc
	v_ldexp_f32 v12, v12, v13
	v_log_f32_e32 v12, v12
	s_nop 0
	v_mul_f32_e32 v13, 0x3f317217, v12
	v_fma_f32 v13, v12, s38, -v13
	v_fmac_f32_e32 v13, 0x3377d1cf, v12
	v_fmac_f32_e32 v13, 0x3f317217, v12
	v_cmp_lt_f32_e64 s[0:1], |v12|, s39
	s_nop 1
	v_cndmask_b32_e64 v12, v12, v13, s[0:1]
	v_cndmask_b32_e32 v13, 0, v185, vcc
	v_sub_f32_e32 v12, v12, v13
	s_mov_b32 s0, 0xd000
	v_sub_f32_e32 v11, v11, v12
	v_add_co_u32_e32 v12, vcc, s0, v2
	v_fmamk_f32 v11, v11, 0x3d800000, v42
	s_nop 0
	v_addc_co_u32_e32 v13, vcc, 0, v3, vcc
	v_lshl_add_u32 v13, v0, 2, 0
	ds_write_b32 v13, v6 offset:16384
	ds_write_b32 v13, v7 offset:24576
	ds_write_b32 v13, v5 offset:32768
	v_sub_f32_e32 v6, v11, v6
	v_mul_f32_e32 v6, 0x3fb8aa3b, v6
	v_exp_f32_e32 v6, v6
	v_lshl_add_u32 v12, v0, 6, 0
	v_mul_f32_e32 v7, v7, v14
	ds_write_b32 v12, v7
	v_mul_f32_e32 v5, v6, v5
	ds_write_b32 v12, v5 offset:32
	ds_write_b32 v13, v9 offset:16640
	ds_write_b32 v13, v10 offset:24832
	ds_write_b32 v13, v8 offset:33024
	v_mul_f32_e32 v5, 0x3fb8aa3b, v9
	v_exp_f32_e32 v5, v5
	v_lshlrev_b32_e32 v2, 16, v248
	v_mul_f32_e32 v5, v10, v5
	ds_write_b32 v12, v5 offset:4
	v_sub_f32_e32 v5, v11, v9
	v_mul_f32_e32 v5, 0x3fb8aa3b, v5
	v_exp_f32_e32 v5, v5
	v_mul_f32_e32 v2, 0x3e000000, v2
	v_lshlrev_b32_e32 v3, 16, v249
	v_mul_f32_e32 v5, v5, v8
	ds_write_b32 v12, v5 offset:36
	ds_write_b32 v13, v30 offset:16896
	ds_write_b32 v13, v31 offset:25088
	ds_write_b32 v13, v29 offset:33280
	v_mul_f32_e32 v5, 0x3fb8aa3b, v30
	v_exp_f32_e32 v5, v5
	s_nop 0
	v_mul_f32_e32 v5, v31, v5
	ds_write_b32 v12, v5 offset:8
	v_sub_f32_e32 v5, v11, v30
	v_mul_f32_e32 v5, 0x3fb8aa3b, v5
	v_exp_f32_e32 v5, v5
	s_nop 0
	v_mul_f32_e32 v5, v5, v29
	ds_write_b32 v12, v5 offset:40
	ds_write_b32 v13, v33 offset:17152
	ds_write_b32 v13, v34 offset:25344
	ds_write_b32 v13, v32 offset:33536
	v_mul_f32_e32 v5, 0x3fb8aa3b, v33
	v_exp_f32_e32 v5, v5
	s_nop 0
	v_mul_f32_e32 v5, v34, v5
	ds_write_b32 v12, v5 offset:12
	v_sub_f32_e32 v5, v11, v33
	v_mul_f32_e32 v5, 0x3fb8aa3b, v5
	v_exp_f32_e32 v5, v5
	s_nop 0
	v_mul_f32_e32 v5, v5, v32
	ds_write_b32 v12, v5 offset:44
	ds_write_b32 v13, v36 offset:17408
	ds_write_b32 v13, v37 offset:25600
	ds_write_b32 v13, v35 offset:33792
	v_mul_f32_e32 v5, 0x3fb8aa3b, v36
	v_exp_f32_e32 v5, v5
	s_nop 0
	v_mul_f32_e32 v5, v37, v5
	ds_write_b32 v12, v5 offset:16
	v_sub_f32_e32 v5, v11, v36
	v_mul_f32_e32 v5, 0x3fb8aa3b, v5
	v_exp_f32_e32 v5, v5
	s_nop 0
	v_mul_f32_e32 v5, v5, v35
	ds_write_b32 v12, v5 offset:48
	ds_write_b32 v13, v39 offset:17664
	ds_write_b32 v13, v40 offset:25856
	ds_write_b32 v13, v38 offset:34048
	v_mul_f32_e32 v5, 0x3fb8aa3b, v39
	v_exp_f32_e32 v5, v5
	s_nop 0
	v_mul_f32_e32 v5, v40, v5
	ds_write_b32 v12, v5 offset:20
	v_sub_f32_e32 v5, v11, v39
	v_mul_f32_e32 v5, 0x3fb8aa3b, v5
	v_exp_f32_e32 v5, v5
	s_nop 0
	v_mul_f32_e32 v5, v5, v38
	ds_write_b32 v12, v5 offset:52
	ds_write_b32 v13, v42 offset:17920
	ds_write_b32 v13, v43 offset:26112
	ds_write_b32 v13, v41 offset:34304
	v_mul_f32_e32 v5, 0x3fb8aa3b, v42
	v_exp_f32_e32 v5, v5
	s_nop 0
	v_mul_f32_e32 v5, v43, v5
	ds_write_b32 v12, v5 offset:24
	v_sub_f32_e32 v5, v11, v42
	v_mul_f32_e32 v5, 0x3fb8aa3b, v5
	v_exp_f32_e32 v5, v5
	s_nop 0
	v_mul_f32_e32 v5, v5, v41
	ds_write_b32 v12, v5 offset:56
	ds_write_b32 v13, v11 offset:18176
	ds_write_b32 v13, v2 offset:26368
	ds_write_b32 v13, v3 offset:34560
	v_mul_f32_e32 v5, 0x3fb8aa3b, v11
	v_exp_f32_e32 v5, v5
	s_nop 0
	v_mul_f32_e32 v2, v2, v5
	ds_write_b32 v12, v2 offset:28
	v_sub_f32_e32 v2, v11, v11
	v_mul_f32_e32 v2, 0x3fb8aa3b, v2
	v_exp_f32_e32 v2, v2
	s_nop 0
	v_mul_f32_e32 v2, v2, v3
	ds_write_b32 v12, v2 offset:60
	ds_write_b32 v13, v5 offset:40960
	v_mov_b32_e32 v22, v152
	v_mov_b32_e32 v23, v153
	v_mov_b32_e32 v24, v154
	v_mov_b32_e32 v25, v155
	v_mov_b32_e32 v44, v244
	v_mov_b32_e32 v45, v245
	v_mov_b32_e32 v46, v246
	v_mov_b32_e32 v47, v247

; __device__ __forceinline__ unsigned pk2(float lo, float hi) { return pg8::cvt_pk_bf16(lo, hi); }
; __device__ __forceinline__ void row_pass(const Params& p, int mode, float coef, const float* nw, int nsplit) {
;     ...
;             float q = 0.f;
; #pragma unroll
;             for (int j = 0; j < 4; ++j) q += (fv[j][0] * fv[j][0] + fv[j][1] * fv[j][1]) + (fv[j][2] * fv[j][2] + fv[j][3] * fv[j][3]);
;             q = wave_sum(q);
;             const float rstd = rsqrtf(q * (1.0f / D) + EPS) * coef; const f32x4* W4 = (const f32x4*)nw;
; #pragma unroll
;             for (int j = 0; j < 4; ++j) { const f32x4 xv = (f32x4){bf2f(xw[j].x & 0xffffu), bf2f(xw[j].x >> 16), bf2f(xw[j].y & 0xffffu), bf2f(xw[j].y >> 16)};
;                 v[j] = xv + fv[j] * W4[64 * j + lane] * rstd; }
;         }
;         if (mode == 2) { f32x4* X4 = (f32x4*)(p.out + (size_t)r * D);
; #pragma unroll
;             for (int j = 0; j < 4; ++j) X4[64 * j + lane] = v[j];
;         } else {
;             float s = 0.f;
; #pragma unroll
;             for (int j = 0; j < 4; ++j) s += (v[j][0] * v[j][0] + v[j][1] * v[j][1]) + (v[j][2] * v[j][2] + v[j][3] * v[j][3]);
;             s = wave_sum(s);
; #pragma unroll
;             for (int j = 0; j < 4; ++j) { u32x2 w; w.x = pk2(v[j][0], v[j][1]); w.y = pk2(v[j][2], v[j][3]); B2[64 * j + lane] = w; }
;             if (lane == 0) RS[r] = rsqrtf(s * (1.0f / D) + EPS);
.LBB0_1460:
	s_or_b64 exec, exec, s[14:15]
	v_pk_mul_f32 v[52:53], v[40:41], v[40:41]
	v_pk_mul_f32 v[54:55], v[38:39], v[38:39]
	v_pk_mul_f32 v[44:45], v[36:37], v[36:37]
	v_pk_mov_b32 v[56:57], v[54:55], v[52:53] op_sel:[1,0]
	v_mov_b32_e32 v55, v53
	v_pk_add_f32 v[52:53], v[56:57], v[54:55]
	global_load_dwordx4 v[186:189], v[6:7], off
	global_load_dwordx4 v[190:193], v[8:9], off
	global_load_dwordx4 v[194:197], v[10:11], off
	global_load_dwordx4 v[198:201], v[12:13], off
	v_pk_mul_f32 v[50:51], v[34:35], v[34:35]
	v_mul_f32_e32 v16, v2, v2
	v_pk_mov_b32 v[54:55], v[50:51], v[44:45] op_sel:[1,0]
	v_mov_b32_e32 v51, v45
	v_pk_add_f32 v[44:45], v[54:55], v[50:51]
	v_pk_fma_f32 v[50:51], v[2:3], v[2:3], v[16:17] op_sel_hi:[1,1,0]
	v_mul_f32_e32 v16, v28, v28
	v_pk_add_f32 v[52:53], v[52:53], v[52:53] op_sel_hi:[0,1]
	v_pk_add_f32 v[44:45], v[44:45], v[44:45] op_sel_hi:[0,1]
	v_pk_fma_f32 v[54:55], v[28:29], v[28:29], v[16:17] op_sel_hi:[1,1,0]
	v_mul_f32_e32 v50, v24, v24
	v_mul_f32_e32 v54, v25, v25
	v_mul_f32_e32 v52, v26, v26
	v_mul_f32_e32 v44, v27, v27
	v_pk_add_f32 v[50:51], v[50:51], v[54:55]
	v_pk_add_f32 v[44:45], v[52:53], v[44:45]
	s_waitcnt vmcnt(0)
	v_pk_mul_f32 v[40:41], v[40:41], v[188:189]
	v_pk_add_f32 v[44:45], v[50:51], v[44:45]
	v_pk_mul_f32 v[56:57], v[38:39], v[186:187]
	v_add_f32_e32 v16, v44, v45
	v_and_b32_e32 v45, 0xffff0000, v42
	s_nop 0
	v_add_f32_dpp v16, v16, v16 quad_perm:[1,0,3,2] row_mask:0xf bank_mask:0xf
	s_nop 1
	v_add_f32_dpp v16, v16, v16 quad_perm:[2,3,0,1] row_mask:0xf bank_mask:0xf
	s_nop 1
	v_add_f32_dpp v16, v16, v16 row_ror:4 row_mask:0xf bank_mask:0xf
	s_nop 1
	v_add_f32_dpp v16, v16, v16 row_ror:8 row_mask:0xf bank_mask:0xf
	s_nop 1
	v_add_f32_dpp v16, v16, v16 row_bcast:15 row_mask:0xa bank_mask:0xf
	s_nop 1
	v_add_f32_dpp v16, v16, v16 row_bcast:31 row_mask:0xc bank_mask:0xf
	s_nop 0
	v_readlane_b32 s16, v16, 63
	v_mov_b32_e32 v44, 0x358637bd
	s_nop 0
	v_mov_b32_e32 v16, s16
	v_fmamk_f32 v16, v16, 0x3a800000, v44
	v_cmp_gt_f32_e32 vcc, s33, v16
	v_mul_f32_e32 v44, 0x4b800000, v16
	s_nop 0
	v_cndmask_b32_e32 v16, v16, v44, vcc
	v_rsq_f32_e32 v16, v16
	s_nop 0
	v_mul_f32_e32 v44, 0x45800000, v16
	v_cndmask_b32_e32 v16, v16, v44, vcc
	v_lshlrev_b32_e32 v44, 16, v42
	v_lshlrev_b32_e32 v42, 16, v43
	v_and_b32_e32 v43, 0xffff0000, v43
	v_pk_fma_f32 v[38:39], v[40:41], v[16:17], v[42:43] op_sel_hi:[1,0,1]
	v_pk_fma_f32 v[40:41], v[56:57], v[16:17], v[44:45] op_sel_hi:[1,0,1]
	v_lshlrev_b32_e32 v56, 16, v32
	v_and_b32_e32 v57, 0xffff0000, v32
	v_lshlrev_b32_e32 v32, 16, v33
	v_and_b32_e32 v33, 0xffff0000, v33
	v_pk_mul_f32 v[36:37], v[36:37], v[192:193]
	v_pk_mul_f32 v[34:35], v[34:35], v[190:191]
	v_pk_fma_f32 v[32:33], v[36:37], v[16:17], v[32:33] op_sel_hi:[1,0,1]
	v_lshlrev_b32_e32 v36, 16, v30
	v_and_b32_e32 v37, 0xffff0000, v30
	v_lshlrev_b32_e32 v30, 16, v31
	v_and_b32_e32 v31, 0xffff0000, v31
	v_pk_fma_f32 v[34:35], v[34:35], v[16:17], v[56:57] op_sel_hi:[1,0,1]
	v_pk_mul_f32 v[28:29], v[28:29], v[196:197]
	v_pk_mul_f32 v[2:3], v[2:3], v[194:195]
	v_pk_fma_f32 v[28:29], v[28:29], v[16:17], v[30:31] op_sel_hi:[1,0,1]
	v_pk_fma_f32 v[30:31], v[2:3], v[16:17], v[36:37] op_sel_hi:[1,0,1]
	v_lshlrev_b32_e32 v36, 16, v0
	v_and_b32_e32 v37, 0xffff0000, v0
	v_lshlrev_b32_e32 v42, 16, v1
	v_and_b32_e32 v43, 0xffff0000, v1
	v_pk_mul_f32 v[0:1], v[24:25], v[198:199]
	s_nop 0
	v_pk_fma_f32 v[24:25], v[0:1], v[16:17], v[36:37] op_sel_hi:[1,0,1]
	v_mul_f32_e32 v0, v41, v41
	v_mul_f32_e32 v1, v39, v39
	v_pk_mul_f32 v[2:3], v[26:27], v[200:201]
	v_fmac_f32_e32 v0, v40, v40
	v_fmac_f32_e32 v1, v38, v38
	v_pk_fma_f32 v[2:3], v[2:3], v[16:17], v[42:43] op_sel_hi:[1,0,1]
	v_add_f32_e32 v0, v0, v1
	v_mul_f32_e32 v1, v35, v35
	v_mul_f32_e32 v16, v33, v33
	v_fmac_f32_e32 v1, v34, v34
	v_fmac_f32_e32 v16, v32, v32
	v_add_f32_e32 v1, v1, v16
	v_add_f32_e32 v0, v0, v1
	v_mul_f32_e32 v1, v31, v31
	v_mul_f32_e32 v16, v29, v29
	v_fmac_f32_e32 v1, v30, v30
	v_fmac_f32_e32 v16, v28, v28
	v_add_f32_e32 v1, v1, v16
	v_add_f32_e32 v0, v1, v0
	v_mul_f32_e32 v1, v25, v25
	v_mul_f32_e32 v16, v3, v3
	v_fmac_f32_e32 v1, v24, v24
	v_fmac_f32_e32 v16, v2, v2
	v_add_f32_e32 v1, v1, v16
	v_add_f32_e32 v0, v1, v0
	v_cvt_pk_bf16_f32 v26, v40, v41
	v_cvt_pk_bf16_f32 v27, v38, v39
	v_add_f32_dpp v0, v0, v0 quad_perm:[1,0,3,2] row_mask:0xf bank_mask:0xf
	global_store_dwordx2 v[22:23], v[26:27], off
	s_nop 0
	v_add_f32_dpp v0, v0, v0 quad_perm:[2,3,0,1] row_mask:0xf bank_mask:0xf
	v_cvt_pk_bf16_f32 v26, v34, v35
	v_cvt_pk_bf16_f32 v27, v32, v33
	v_add_f32_dpp v0, v0, v0 row_ror:4 row_mask:0xf bank_mask:0xf
	global_store_dwordx2 v[22:23], v[26:27], off offset:512
	s_nop 0
	v_add_f32_dpp v0, v0, v0 row_ror:8 row_mask:0xf bank_mask:0xf
	v_cvt_pk_bf16_f32 v26, v30, v31
	v_cvt_pk_bf16_f32 v27, v28, v29
	v_add_f32_dpp v0, v0, v0 row_bcast:15 row_mask:0xa bank_mask:0xf
	global_store_dwordx2 v[22:23], v[26:27], off offset:1024
	s_nop 0
	v_add_f32_dpp v0, v0, v0 row_bcast:31 row_mask:0xc bank_mask:0xf
	v_cvt_pk_bf16_f32 v24, v24, v25
	v_cvt_pk_bf16_f32 v25, v2, v3
	global_store_dwordx2 v[22:23], v[24:25], off offset:1536
	v_readlane_b32 s16, v0, 63
	s_and_saveexec_b64 s[14:15], s[10:11]
	v_mov_b32_e32 v44, v196
	v_mov_b32_e32 v45, v197
	v_mov_b32_e32 v58, v188
	v_mov_b32_e32 v59, v189
	s_cbranch_execz .LBB0_1441
	v_mov_b32_e32 v0, s16
	v_mov_b32_e32 v1, 0x358637bd
	v_fmamk_f32 v0, v0, 0x3a800000, v1
	v_mul_f32_e32 v1, 0x4b800000, v0
	v_cmp_gt_f32_e32 vcc, s33, v0
	v_readlane_b32 s16, v252, 39
	v_readlane_b32 s17, v252, 40
	v_cndmask_b32_e32 v0, v0, v1, vcc
	v_rsq_f32_e32 v0, v0
	s_nop 0
	v_mul_f32_e32 v1, 0x45800000, v0
	v_cndmask_b32_e32 v2, v0, v1, vcc
	v_lshl_add_u64 v[0:1], v[20:21], 2, s[16:17]
	global_store_dword v[0:1], v2, off
	s_branch .LBB0_1441
